# all s_setprio removed from the seven K-loops (priority flips are not load-bearing; saves the issue slots at the interval boundaries)
# speedup vs baseline: 1.0005x; 1.0005x over previous
.LBB0_110:
	s_add_u32 vcc_lo, s78, 0x160080
	s_addc_u32 vcc_hi, s79, 0
	s_add_u32 s84, s76, 0x100
	s_addc_u32 s85, s77, 0
	s_mov_b32 s93, -2
	s_add_u32 s72, vcc_lo, 0xffea0080
	s_addc_u32 s73, vcc_hi, -1
	s_add_i32 s95, 0, 0x10000
	s_cmp_eq_u32 s93, 12
	s_cselect_b32 s79, s1, s73
	s_cselect_b32 s78, s0, s72
	v_add_u32_e32 v26, s95, v186
	s_cselect_b32 s77, s89, s85
	s_cselect_b32 s76, s88, s84
	s_add_i32 s12, 0, 0x14000
	ds_read_b128 v[36:39], v26
	ds_read_b128 v[56:59], v26 offset:1024
	ds_read_b128 v[84:87], v26 offset:2048
	ds_read_b128 v[104:107], v26 offset:3072
	v_add_u32_e32 v26, s12, v186
	ds_read_b128 v[124:127], v26
	ds_read_b128 v[144:147], v26 offset:1024
	ds_read_b128 v[156:159], v26 offset:2048
	ds_read_b128 v[180:183], v26 offset:3072
	v_lshl_add_u64 v[226:227], vcc, 0, v[176:177]
	s_add_i32 m0, s17, 0xc000
	ds_read_b128 v[190:193], v188
	ds_read_b128 v[194:197], v188 offset:1024
	ds_read_b128 v[198:201], v188 offset:2048
	ds_read_b128 v[202:205], v188 offset:3072
	ds_read_b128 v[206:209], v188 offset:4096
	ds_read_b128 v[210:213], v188 offset:5120
	ds_read_b128 v[214:217], v188 offset:6144
	ds_read_b128 v[218:221], v188 offset:7168
	global_load_lds_dwordx4 v[226:227], off
	v_lshl_add_u64 v[226:227], vcc, 0, v[178:179]
	s_add_i32 m0, s17, 0xe000
	s_nop 0
	global_load_lds_dwordx4 v[226:227], off
	s_waitcnt vmcnt(8)
	s_waitcnt lgkmcnt(0)
	s_barrier
	v_mfma_f32_16x16x32_bf16 v[148:151], v[36:39], v[190:193], 0
	v_mfma_f32_16x16x32_bf16 v[152:155], v[84:87], v[190:193], 0
	v_mfma_f32_16x16x32_bf16 v[128:131], v[36:39], v[198:201], 0
	v_mfma_f32_16x16x32_bf16 v[132:135], v[84:87], v[198:201], 0
	v_mfma_f32_16x16x32_bf16 v[108:111], v[36:39], v[206:209], 0
	v_mfma_f32_16x16x32_bf16 v[112:115], v[84:87], v[206:209], 0
	v_mfma_f32_16x16x32_bf16 v[88:91], v[36:39], v[214:217], 0
	v_mfma_f32_16x16x32_bf16 v[92:95], v[84:87], v[214:217], 0
	v_mfma_f32_16x16x32_bf16 v[148:151], v[56:59], v[194:197], v[148:151]
	v_mfma_f32_16x16x32_bf16 v[152:155], v[104:107], v[194:197], v[152:155]
	v_mfma_f32_16x16x32_bf16 v[128:131], v[56:59], v[202:205], v[128:131]
	v_mfma_f32_16x16x32_bf16 v[132:135], v[104:107], v[202:205], v[132:135]
	v_mfma_f32_16x16x32_bf16 v[108:111], v[56:59], v[210:213], v[108:111]
	v_mfma_f32_16x16x32_bf16 v[112:115], v[104:107], v[210:213], v[112:115]
	v_mfma_f32_16x16x32_bf16 v[88:91], v[56:59], v[218:221], v[88:91]
	v_mfma_f32_16x16x32_bf16 v[92:95], v[104:107], v[218:221], v[92:95]
	v_mfma_f32_16x16x32_bf16 v[140:143], v[124:127], v[190:193], 0
	v_mfma_f32_16x16x32_bf16 v[136:139], v[156:159], v[190:193], 0
	v_mfma_f32_16x16x32_bf16 v[120:123], v[124:127], v[198:201], 0
	v_mfma_f32_16x16x32_bf16 v[116:119], v[156:159], v[198:201], 0
	v_mfma_f32_16x16x32_bf16 v[100:103], v[124:127], v[206:209], 0
	v_mfma_f32_16x16x32_bf16 v[96:99], v[156:159], v[206:209], 0
	v_mfma_f32_16x16x32_bf16 v[80:83], v[124:127], v[214:217], 0
	v_mfma_f32_16x16x32_bf16 v[76:79], v[156:159], v[214:217], 0
	v_mfma_f32_16x16x32_bf16 v[140:143], v[144:147], v[194:197], v[140:143]
	v_mfma_f32_16x16x32_bf16 v[136:139], v[180:183], v[194:197], v[136:139]
	v_mfma_f32_16x16x32_bf16 v[120:123], v[144:147], v[202:205], v[120:123]
	v_mfma_f32_16x16x32_bf16 v[116:119], v[180:183], v[202:205], v[116:119]
	v_mfma_f32_16x16x32_bf16 v[100:103], v[144:147], v[210:213], v[100:103]
	v_mfma_f32_16x16x32_bf16 v[96:99], v[180:183], v[210:213], v[96:99]
	v_mfma_f32_16x16x32_bf16 v[80:83], v[144:147], v[218:221], v[80:83]
	v_mfma_f32_16x16x32_bf16 v[76:79], v[180:183], v[218:221], v[76:79]
	s_barrier
	s_add_i32 s72, s95, s16
	v_lshl_add_u64 v[226:227], s[76:77], 0, v[164:165]
	s_mov_b32 m0, s72
	ds_read_b128 v[190:193], v188 offset:16384
	ds_read_b128 v[194:197], v188 offset:17408
	ds_read_b128 v[198:201], v188 offset:18432
	ds_read_b128 v[202:205], v188 offset:19456
	ds_read_b128 v[206:209], v188 offset:20480
	ds_read_b128 v[210:213], v188 offset:21504
	ds_read_b128 v[214:217], v188 offset:22528
	ds_read_b128 v[218:221], v188 offset:23552
	global_load_lds_dwordx4 v[226:227], off
	s_add_i32 m0, s72, 0x2000
	s_add_u32 s72, s76, 0x40000
	v_lshl_add_u64 v[228:229], s[76:77], 0, v[160:161]
	s_addc_u32 s73, s77, 0
	s_add_i32 s12, s12, s16
	global_load_lds_dwordx4 v[228:229], off
	v_lshl_add_u64 v[230:231], s[72:73], 0, v[164:165]
	s_mov_b32 m0, s12
	v_lshl_add_u64 v[232:233], s[78:79], 0, v[162:163]
	global_load_lds_dwordx4 v[230:231], off
	v_lshl_add_u64 v[230:231], s[72:73], 0, v[160:161]
	s_add_i32 m0, s12, 0x2000
	s_nop 0
	global_load_lds_dwordx4 v[230:231], off
	v_lshl_add_u64 v[230:231], s[78:79], 0, v[166:167]
	s_mov_b32 m0, s17
	s_nop 0
	global_load_lds_dwordx4 v[230:231], off
	s_mov_b32 m0, s46
	s_nop 0
	global_load_lds_dwordx4 v[232:233], off
	s_waitcnt vmcnt(8)
	s_waitcnt lgkmcnt(0)
	s_barrier
	v_mfma_f32_16x16x32_bf16 v[68:71], v[36:39], v[190:193], 0
	v_mfma_f32_16x16x32_bf16 v[72:75], v[84:87], v[190:193], 0
	v_mfma_f32_16x16x32_bf16 v[48:51], v[36:39], v[198:201], 0
	v_mfma_f32_16x16x32_bf16 v[52:55], v[84:87], v[198:201], 0
	v_mfma_f32_16x16x32_bf16 v[28:31], v[36:39], v[206:209], 0
	v_mfma_f32_16x16x32_bf16 v[32:35], v[84:87], v[206:209], 0
	v_mfma_f32_16x16x32_bf16 v[10:13], v[36:39], v[214:217], 0
	v_mfma_f32_16x16x32_bf16 v[14:17], v[84:87], v[214:217], 0
	v_mfma_f32_16x16x32_bf16 v[68:71], v[56:59], v[194:197], v[68:71]
	v_mfma_f32_16x16x32_bf16 v[72:75], v[104:107], v[194:197], v[72:75]
	v_mfma_f32_16x16x32_bf16 v[48:51], v[56:59], v[202:205], v[48:51]
	v_mfma_f32_16x16x32_bf16 v[52:55], v[104:107], v[202:205], v[52:55]
	v_mfma_f32_16x16x32_bf16 v[28:31], v[56:59], v[210:213], v[28:31]
	v_mfma_f32_16x16x32_bf16 v[32:35], v[104:107], v[210:213], v[32:35]
	v_mfma_f32_16x16x32_bf16 v[10:13], v[56:59], v[218:221], v[10:13]
	v_mfma_f32_16x16x32_bf16 v[14:17], v[104:107], v[218:221], v[14:17]
	v_mfma_f32_16x16x32_bf16 v[44:47], v[124:127], v[198:201], 0
	v_mfma_f32_16x16x32_bf16 v[40:43], v[156:159], v[198:201], 0
	v_mfma_f32_16x16x32_bf16 v[22:25], v[124:127], v[206:209], 0
	v_mfma_f32_16x16x32_bf16 v[18:21], v[156:159], v[206:209], 0
	v_mfma_f32_16x16x32_bf16 v[2:5], v[124:127], v[214:217], 0
	v_mfma_f32_16x16x32_bf16 v[6:9], v[156:159], v[214:217], 0
	v_mfma_f32_16x16x32_bf16 v[36:39], v[124:127], v[190:193], 0
	v_mfma_f32_16x16x32_bf16 v[56:59], v[156:159], v[190:193], 0
	v_mfma_f32_16x16x32_bf16 v[44:47], v[144:147], v[202:205], v[44:47]
	v_mfma_f32_16x16x32_bf16 v[40:43], v[180:183], v[202:205], v[40:43]
	v_mfma_f32_16x16x32_bf16 v[22:25], v[144:147], v[210:213], v[22:25]
	v_mfma_f32_16x16x32_bf16 v[18:21], v[180:183], v[210:213], v[18:21]
	v_mfma_f32_16x16x32_bf16 v[2:5], v[144:147], v[218:221], v[2:5]
	v_mfma_f32_16x16x32_bf16 v[6:9], v[180:183], v[218:221], v[6:9]
	v_mfma_f32_16x16x32_bf16 v[36:39], v[144:147], v[194:197], v[36:39]
	v_mfma_f32_16x16x32_bf16 v[56:59], v[180:183], v[194:197], v[56:59]
	s_barrier
	s_add_i32 s12, 0, 0x18000
	v_add_u32_e32 v26, s12, v186
	s_add_i32 s95, 0, 0x1c000
	ds_read_b128 v[60:63], v26
	ds_read_b128 v[64:67], v26 offset:1024
	ds_read_b128 v[84:87], v26 offset:2048
	ds_read_b128 v[104:107], v26 offset:3072
	v_add_u32_e32 v26, s95, v186
	ds_read_b128 v[124:127], v26
	ds_read_b128 v[144:147], v26 offset:1024
	ds_read_b128 v[156:159], v26 offset:2048
	ds_read_b128 v[180:183], v26 offset:3072
	s_add_u32 s72, s78, 0x160000
	s_addc_u32 s73, s79, 0
	s_mov_b32 m0, s47
	v_lshl_add_u64 v[234:235], s[72:73], 0, v[166:167]
	ds_read_b128 v[190:193], v188 offset:32768
	ds_read_b128 v[194:197], v188 offset:33792
	ds_read_b128 v[198:201], v188 offset:34816
	ds_read_b128 v[202:205], v188 offset:35840
	ds_read_b128 v[206:209], v188 offset:36864
	ds_read_b128 v[210:213], v188 offset:37888
	ds_read_b128 v[214:217], v188 offset:38912
	ds_read_b128 v[218:221], v188 offset:39936
	global_load_lds_dwordx4 v[234:235], off
	v_lshl_add_u64 v[234:235], s[72:73], 0, v[162:163]
	s_mov_b32 m0, s8
	s_nop 0
	global_load_lds_dwordx4 v[234:235], off
	s_waitcnt vmcnt(8)
	s_waitcnt lgkmcnt(0)
	s_barrier
	v_mfma_f32_16x16x32_bf16 v[148:151], v[60:63], v[190:193], v[148:151]
	v_mfma_f32_16x16x32_bf16 v[152:155], v[84:87], v[190:193], v[152:155]
	v_mfma_f32_16x16x32_bf16 v[128:131], v[60:63], v[198:201], v[128:131]
	v_mfma_f32_16x16x32_bf16 v[132:135], v[84:87], v[198:201], v[132:135]
	v_mfma_f32_16x16x32_bf16 v[108:111], v[60:63], v[206:209], v[108:111]
	v_mfma_f32_16x16x32_bf16 v[112:115], v[84:87], v[206:209], v[112:115]
	v_mfma_f32_16x16x32_bf16 v[88:91], v[60:63], v[214:217], v[88:91]
	v_mfma_f32_16x16x32_bf16 v[92:95], v[84:87], v[214:217], v[92:95]
	v_mfma_f32_16x16x32_bf16 v[148:151], v[64:67], v[194:197], v[148:151]
	v_mfma_f32_16x16x32_bf16 v[152:155], v[104:107], v[194:197], v[152:155]
	v_mfma_f32_16x16x32_bf16 v[128:131], v[64:67], v[202:205], v[128:131]
	v_mfma_f32_16x16x32_bf16 v[132:135], v[104:107], v[202:205], v[132:135]
	v_mfma_f32_16x16x32_bf16 v[108:111], v[64:67], v[210:213], v[108:111]
	v_mfma_f32_16x16x32_bf16 v[112:115], v[104:107], v[210:213], v[112:115]
	v_mfma_f32_16x16x32_bf16 v[88:91], v[64:67], v[218:221], v[88:91]
	v_mfma_f32_16x16x32_bf16 v[92:95], v[104:107], v[218:221], v[92:95]
	v_mfma_f32_16x16x32_bf16 v[140:143], v[124:127], v[190:193], v[140:143]
	v_mfma_f32_16x16x32_bf16 v[136:139], v[156:159], v[190:193], v[136:139]
	v_mfma_f32_16x16x32_bf16 v[120:123], v[124:127], v[198:201], v[120:123]
	v_mfma_f32_16x16x32_bf16 v[116:119], v[156:159], v[198:201], v[116:119]
	v_mfma_f32_16x16x32_bf16 v[100:103], v[124:127], v[206:209], v[100:103]
	v_mfma_f32_16x16x32_bf16 v[96:99], v[156:159], v[206:209], v[96:99]
	v_mfma_f32_16x16x32_bf16 v[80:83], v[124:127], v[214:217], v[80:83]
	v_mfma_f32_16x16x32_bf16 v[76:79], v[156:159], v[214:217], v[76:79]
	v_mfma_f32_16x16x32_bf16 v[140:143], v[144:147], v[194:197], v[140:143]
	v_mfma_f32_16x16x32_bf16 v[136:139], v[180:183], v[194:197], v[136:139]
	v_mfma_f32_16x16x32_bf16 v[120:123], v[144:147], v[202:205], v[120:123]
	v_mfma_f32_16x16x32_bf16 v[116:119], v[180:183], v[202:205], v[116:119]
	v_mfma_f32_16x16x32_bf16 v[100:103], v[144:147], v[210:213], v[100:103]
	v_mfma_f32_16x16x32_bf16 v[96:99], v[180:183], v[210:213], v[96:99]
	v_mfma_f32_16x16x32_bf16 v[80:83], v[144:147], v[218:221], v[80:83]
	v_mfma_f32_16x16x32_bf16 v[76:79], v[180:183], v[218:221], v[76:79]
	s_barrier
	s_add_i32 s12, s12, s16
	v_lshl_add_u64 v[226:227], v[226:227], 0, s[82:83]
	s_mov_b32 m0, s12
	ds_read_b128 v[190:193], v188 offset:49152
	ds_read_b128 v[194:197], v188 offset:50176
	ds_read_b128 v[198:201], v188 offset:51200
	ds_read_b128 v[202:205], v188 offset:52224
	ds_read_b128 v[206:209], v188 offset:53248
	ds_read_b128 v[210:213], v188 offset:54272
	ds_read_b128 v[214:217], v188 offset:55296
	ds_read_b128 v[218:221], v188 offset:56320
	global_load_lds_dwordx4 v[226:227], off
	s_add_i32 m0, s12, 0x2000
	s_add_u32 s72, s76, 0x40080
	v_lshl_add_u64 v[226:227], v[228:229], 0, s[82:83]
	s_addc_u32 s73, s77, 0
	s_add_i32 s12, s95, s16
	global_load_lds_dwordx4 v[226:227], off
	v_lshl_add_u64 v[226:227], s[72:73], 0, v[164:165]
	s_mov_b32 m0, s12
	s_nop 0
	global_load_lds_dwordx4 v[226:227], off
	v_lshl_add_u64 v[226:227], s[72:73], 0, v[160:161]
	s_add_i32 m0, s12, 0x2000
	s_nop 0
	global_load_lds_dwordx4 v[226:227], off
	v_lshl_add_u64 v[226:227], v[230:231], 0, s[82:83]
	s_mov_b32 m0, s22
	s_nop 0
	global_load_lds_dwordx4 v[226:227], off
	v_lshl_add_u64 v[226:227], v[232:233], 0, s[82:83]
	s_mov_b32 m0, s80
	s_nop 0
	global_load_lds_dwordx4 v[226:227], off
	s_waitcnt vmcnt(8)
	s_waitcnt lgkmcnt(0)
	s_barrier
	v_mfma_f32_16x16x32_bf16 v[68:71], v[60:63], v[190:193], v[68:71]
	v_mfma_f32_16x16x32_bf16 v[72:75], v[84:87], v[190:193], v[72:75]
	v_mfma_f32_16x16x32_bf16 v[48:51], v[60:63], v[198:201], v[48:51]
	v_mfma_f32_16x16x32_bf16 v[52:55], v[84:87], v[198:201], v[52:55]
	v_mfma_f32_16x16x32_bf16 v[28:31], v[60:63], v[206:209], v[28:31]
	v_mfma_f32_16x16x32_bf16 v[32:35], v[84:87], v[206:209], v[32:35]
	v_mfma_f32_16x16x32_bf16 v[10:13], v[60:63], v[214:217], v[10:13]
	v_mfma_f32_16x16x32_bf16 v[14:17], v[84:87], v[214:217], v[14:17]
	v_mfma_f32_16x16x32_bf16 v[68:71], v[64:67], v[194:197], v[68:71]
	v_mfma_f32_16x16x32_bf16 v[72:75], v[104:107], v[194:197], v[72:75]
	v_mfma_f32_16x16x32_bf16 v[48:51], v[64:67], v[202:205], v[48:51]
	v_mfma_f32_16x16x32_bf16 v[52:55], v[104:107], v[202:205], v[52:55]
	v_mfma_f32_16x16x32_bf16 v[28:31], v[64:67], v[210:213], v[28:31]
	v_mfma_f32_16x16x32_bf16 v[32:35], v[104:107], v[210:213], v[32:35]
	v_mfma_f32_16x16x32_bf16 v[10:13], v[64:67], v[218:221], v[10:13]
	v_mfma_f32_16x16x32_bf16 v[14:17], v[104:107], v[218:221], v[14:17]
	v_mfma_f32_16x16x32_bf16 v[36:39], v[124:127], v[190:193], v[36:39]
	v_mfma_f32_16x16x32_bf16 v[64:67], v[144:147], v[194:197], v[36:39]
	v_mfma_f32_16x16x32_bf16 v[36:39], v[156:159], v[190:193], v[56:59]
	v_mfma_f32_16x16x32_bf16 v[60:63], v[180:183], v[194:197], v[36:39]
	v_mfma_f32_16x16x32_bf16 v[36:39], v[124:127], v[198:201], v[44:47]
	v_mfma_f32_16x16x32_bf16 v[44:47], v[144:147], v[202:205], v[36:39]
	v_mfma_f32_16x16x32_bf16 v[36:39], v[156:159], v[198:201], v[40:43]
	v_mfma_f32_16x16x32_bf16 v[22:25], v[124:127], v[206:209], v[22:25]
	v_mfma_f32_16x16x32_bf16 v[18:21], v[156:159], v[206:209], v[18:21]
	v_mfma_f32_16x16x32_bf16 v[2:5], v[124:127], v[214:217], v[2:5]
	v_mfma_f32_16x16x32_bf16 v[6:9], v[156:159], v[214:217], v[6:9]
	v_mfma_f32_16x16x32_bf16 v[40:43], v[180:183], v[202:205], v[36:39]
	v_mfma_f32_16x16x32_bf16 v[22:25], v[144:147], v[210:213], v[22:25]
	v_mfma_f32_16x16x32_bf16 v[18:21], v[180:183], v[210:213], v[18:21]
	v_mfma_f32_16x16x32_bf16 v[2:5], v[144:147], v[218:221], v[2:5]
	v_mfma_f32_16x16x32_bf16 v[6:9], v[180:183], v[218:221], v[6:9]
	s_barrier
	s_add_i32 s93, s93, 2
	s_add_u32 vcc_lo, vcc_lo, 0x100
	s_addc_u32 vcc_hi, vcc_hi, 0
	s_add_u32 s84, s84, 0x100
	s_addc_u32 s85, s85, 0
.LBB0_111:
	s_add_u32 s72, vcc_lo, 0xffea0080
	s_addc_u32 s73, vcc_hi, -1
	s_add_i32 s95, 0, 0x10000
	s_cmp_eq_u32 s93, 12
	s_cselect_b32 s79, s1, s73
	s_cselect_b32 s78, s0, s72
	v_add_u32_e32 v26, s95, v186
	s_cselect_b32 s77, s89, s85
	s_cselect_b32 s76, s88, s84
	s_add_i32 s12, 0, 0x14000
	ds_read_b128 v[36:39], v26
	ds_read_b128 v[56:59], v26 offset:1024
	ds_read_b128 v[84:87], v26 offset:2048
	ds_read_b128 v[104:107], v26 offset:3072
	v_add_u32_e32 v26, s12, v186
	ds_read_b128 v[124:127], v26
	ds_read_b128 v[144:147], v26 offset:1024
	ds_read_b128 v[156:159], v26 offset:2048
	ds_read_b128 v[180:183], v26 offset:3072
	v_lshl_add_u64 v[226:227], vcc, 0, v[176:177]
	s_add_i32 m0, s17, 0xc000
	ds_read_b128 v[190:193], v188
	ds_read_b128 v[194:197], v188 offset:1024
	ds_read_b128 v[198:201], v188 offset:2048
	ds_read_b128 v[202:205], v188 offset:3072
	ds_read_b128 v[206:209], v188 offset:4096
	ds_read_b128 v[210:213], v188 offset:5120
	ds_read_b128 v[214:217], v188 offset:6144
	ds_read_b128 v[218:221], v188 offset:7168
	global_load_lds_dwordx4 v[226:227], off
	v_lshl_add_u64 v[226:227], vcc, 0, v[178:179]
	s_add_i32 m0, s17, 0xe000
	s_nop 0
	global_load_lds_dwordx4 v[226:227], off
	s_waitcnt vmcnt(8)
	s_waitcnt lgkmcnt(0)
	s_barrier
	v_mfma_f32_16x16x32_bf16 v[148:151], v[36:39], v[190:193], v[148:151]
	v_mfma_f32_16x16x32_bf16 v[152:155], v[84:87], v[190:193], v[152:155]
	v_mfma_f32_16x16x32_bf16 v[128:131], v[36:39], v[198:201], v[128:131]
	v_mfma_f32_16x16x32_bf16 v[132:135], v[84:87], v[198:201], v[132:135]
	v_mfma_f32_16x16x32_bf16 v[108:111], v[36:39], v[206:209], v[108:111]
	v_mfma_f32_16x16x32_bf16 v[112:115], v[84:87], v[206:209], v[112:115]
	v_mfma_f32_16x16x32_bf16 v[88:91], v[36:39], v[214:217], v[88:91]
	v_mfma_f32_16x16x32_bf16 v[92:95], v[84:87], v[214:217], v[92:95]
	v_mfma_f32_16x16x32_bf16 v[148:151], v[56:59], v[194:197], v[148:151]
	v_mfma_f32_16x16x32_bf16 v[152:155], v[104:107], v[194:197], v[152:155]
	v_mfma_f32_16x16x32_bf16 v[128:131], v[56:59], v[202:205], v[128:131]
	v_mfma_f32_16x16x32_bf16 v[132:135], v[104:107], v[202:205], v[132:135]
	v_mfma_f32_16x16x32_bf16 v[108:111], v[56:59], v[210:213], v[108:111]
	v_mfma_f32_16x16x32_bf16 v[112:115], v[104:107], v[210:213], v[112:115]
	v_mfma_f32_16x16x32_bf16 v[88:91], v[56:59], v[218:221], v[88:91]
	v_mfma_f32_16x16x32_bf16 v[92:95], v[104:107], v[218:221], v[92:95]
	v_mfma_f32_16x16x32_bf16 v[140:143], v[124:127], v[190:193], v[140:143]
	v_mfma_f32_16x16x32_bf16 v[136:139], v[156:159], v[190:193], v[136:139]
	v_mfma_f32_16x16x32_bf16 v[120:123], v[124:127], v[198:201], v[120:123]
	v_mfma_f32_16x16x32_bf16 v[116:119], v[156:159], v[198:201], v[116:119]
	v_mfma_f32_16x16x32_bf16 v[100:103], v[124:127], v[206:209], v[100:103]
	v_mfma_f32_16x16x32_bf16 v[96:99], v[156:159], v[206:209], v[96:99]
	v_mfma_f32_16x16x32_bf16 v[80:83], v[124:127], v[214:217], v[80:83]
	v_mfma_f32_16x16x32_bf16 v[76:79], v[156:159], v[214:217], v[76:79]
	v_mfma_f32_16x16x32_bf16 v[140:143], v[144:147], v[194:197], v[140:143]
	v_mfma_f32_16x16x32_bf16 v[136:139], v[180:183], v[194:197], v[136:139]
	v_mfma_f32_16x16x32_bf16 v[120:123], v[144:147], v[202:205], v[120:123]
	v_mfma_f32_16x16x32_bf16 v[116:119], v[180:183], v[202:205], v[116:119]
	v_mfma_f32_16x16x32_bf16 v[100:103], v[144:147], v[210:213], v[100:103]
	v_mfma_f32_16x16x32_bf16 v[96:99], v[180:183], v[210:213], v[96:99]
	v_mfma_f32_16x16x32_bf16 v[80:83], v[144:147], v[218:221], v[80:83]
	v_mfma_f32_16x16x32_bf16 v[76:79], v[180:183], v[218:221], v[76:79]
	s_barrier
	s_add_i32 s72, s95, s16
	v_lshl_add_u64 v[226:227], s[76:77], 0, v[164:165]
	s_mov_b32 m0, s72
	ds_read_b128 v[190:193], v188 offset:16384
	ds_read_b128 v[194:197], v188 offset:17408
	ds_read_b128 v[198:201], v188 offset:18432
	ds_read_b128 v[202:205], v188 offset:19456
	ds_read_b128 v[206:209], v188 offset:20480
	ds_read_b128 v[210:213], v188 offset:21504
	ds_read_b128 v[214:217], v188 offset:22528
	ds_read_b128 v[218:221], v188 offset:23552
	global_load_lds_dwordx4 v[226:227], off
	s_add_i32 m0, s72, 0x2000
	s_add_u32 s72, s76, 0x40000
	v_lshl_add_u64 v[228:229], s[76:77], 0, v[160:161]
	s_addc_u32 s73, s77, 0
	s_add_i32 s12, s12, s16
	global_load_lds_dwordx4 v[228:229], off
	v_lshl_add_u64 v[230:231], s[72:73], 0, v[164:165]
	s_mov_b32 m0, s12
	v_lshl_add_u64 v[232:233], s[78:79], 0, v[162:163]
	global_load_lds_dwordx4 v[230:231], off
	v_lshl_add_u64 v[230:231], s[72:73], 0, v[160:161]
	s_add_i32 m0, s12, 0x2000
	s_nop 0
	global_load_lds_dwordx4 v[230:231], off
	v_lshl_add_u64 v[230:231], s[78:79], 0, v[166:167]
	s_mov_b32 m0, s17
	s_nop 0
	global_load_lds_dwordx4 v[230:231], off
	s_mov_b32 m0, s46
	s_nop 0
	global_load_lds_dwordx4 v[232:233], off
	s_waitcnt vmcnt(8)
	s_waitcnt lgkmcnt(0)
	s_barrier
	v_mfma_f32_16x16x32_bf16 v[68:71], v[36:39], v[190:193], v[68:71]
	v_mfma_f32_16x16x32_bf16 v[72:75], v[84:87], v[190:193], v[72:75]
	v_mfma_f32_16x16x32_bf16 v[48:51], v[36:39], v[198:201], v[48:51]
	v_mfma_f32_16x16x32_bf16 v[52:55], v[84:87], v[198:201], v[52:55]
	v_mfma_f32_16x16x32_bf16 v[28:31], v[36:39], v[206:209], v[28:31]
	v_mfma_f32_16x16x32_bf16 v[32:35], v[84:87], v[206:209], v[32:35]
	v_mfma_f32_16x16x32_bf16 v[10:13], v[36:39], v[214:217], v[10:13]
	v_mfma_f32_16x16x32_bf16 v[14:17], v[84:87], v[214:217], v[14:17]
	v_mfma_f32_16x16x32_bf16 v[68:71], v[56:59], v[194:197], v[68:71]
	v_mfma_f32_16x16x32_bf16 v[72:75], v[104:107], v[194:197], v[72:75]
	v_mfma_f32_16x16x32_bf16 v[48:51], v[56:59], v[202:205], v[48:51]
	v_mfma_f32_16x16x32_bf16 v[52:55], v[104:107], v[202:205], v[52:55]
	v_mfma_f32_16x16x32_bf16 v[28:31], v[56:59], v[210:213], v[28:31]
	v_mfma_f32_16x16x32_bf16 v[32:35], v[104:107], v[210:213], v[32:35]
	v_mfma_f32_16x16x32_bf16 v[10:13], v[56:59], v[218:221], v[10:13]
	v_mfma_f32_16x16x32_bf16 v[14:17], v[104:107], v[218:221], v[14:17]
	v_mfma_f32_16x16x32_bf16 v[44:47], v[124:127], v[198:201], v[44:47]
	v_mfma_f32_16x16x32_bf16 v[40:43], v[156:159], v[198:201], v[40:43]
	v_mfma_f32_16x16x32_bf16 v[22:25], v[124:127], v[206:209], v[22:25]
	v_mfma_f32_16x16x32_bf16 v[18:21], v[156:159], v[206:209], v[18:21]
	v_mfma_f32_16x16x32_bf16 v[2:5], v[124:127], v[214:217], v[2:5]
	v_mfma_f32_16x16x32_bf16 v[6:9], v[156:159], v[214:217], v[6:9]
	v_mfma_f32_16x16x32_bf16 v[36:39], v[124:127], v[190:193], v[64:67]
	v_mfma_f32_16x16x32_bf16 v[56:59], v[156:159], v[190:193], v[60:63]
	v_mfma_f32_16x16x32_bf16 v[44:47], v[144:147], v[202:205], v[44:47]
	v_mfma_f32_16x16x32_bf16 v[40:43], v[180:183], v[202:205], v[40:43]
	v_mfma_f32_16x16x32_bf16 v[22:25], v[144:147], v[210:213], v[22:25]
	v_mfma_f32_16x16x32_bf16 v[18:21], v[180:183], v[210:213], v[18:21]
	v_mfma_f32_16x16x32_bf16 v[2:5], v[144:147], v[218:221], v[2:5]
	v_mfma_f32_16x16x32_bf16 v[6:9], v[180:183], v[218:221], v[6:9]
	v_mfma_f32_16x16x32_bf16 v[36:39], v[144:147], v[194:197], v[36:39]
	v_mfma_f32_16x16x32_bf16 v[56:59], v[180:183], v[194:197], v[56:59]
	s_barrier
	s_add_i32 s12, 0, 0x18000
	v_add_u32_e32 v26, s12, v186
	s_add_i32 s95, 0, 0x1c000
	ds_read_b128 v[60:63], v26
	ds_read_b128 v[64:67], v26 offset:1024
	ds_read_b128 v[84:87], v26 offset:2048
	ds_read_b128 v[104:107], v26 offset:3072
	v_add_u32_e32 v26, s95, v186
	ds_read_b128 v[124:127], v26
	ds_read_b128 v[144:147], v26 offset:1024
	ds_read_b128 v[156:159], v26 offset:2048
	ds_read_b128 v[180:183], v26 offset:3072
	s_add_u32 s72, s78, 0x160000
	s_addc_u32 s73, s79, 0
	s_mov_b32 m0, s47
	v_lshl_add_u64 v[234:235], s[72:73], 0, v[166:167]
	ds_read_b128 v[190:193], v188 offset:32768
	ds_read_b128 v[194:197], v188 offset:33792
	ds_read_b128 v[198:201], v188 offset:34816
	ds_read_b128 v[202:205], v188 offset:35840
	ds_read_b128 v[206:209], v188 offset:36864
	ds_read_b128 v[210:213], v188 offset:37888
	ds_read_b128 v[214:217], v188 offset:38912
	ds_read_b128 v[218:221], v188 offset:39936
	global_load_lds_dwordx4 v[234:235], off
	v_lshl_add_u64 v[234:235], s[72:73], 0, v[162:163]
	s_mov_b32 m0, s8
	s_nop 0
	global_load_lds_dwordx4 v[234:235], off
	s_waitcnt vmcnt(8)
	s_waitcnt lgkmcnt(0)
	s_barrier
	v_mfma_f32_16x16x32_bf16 v[148:151], v[60:63], v[190:193], v[148:151]
	v_mfma_f32_16x16x32_bf16 v[152:155], v[84:87], v[190:193], v[152:155]
	v_mfma_f32_16x16x32_bf16 v[128:131], v[60:63], v[198:201], v[128:131]
	v_mfma_f32_16x16x32_bf16 v[132:135], v[84:87], v[198:201], v[132:135]
	v_mfma_f32_16x16x32_bf16 v[108:111], v[60:63], v[206:209], v[108:111]
	v_mfma_f32_16x16x32_bf16 v[112:115], v[84:87], v[206:209], v[112:115]
	v_mfma_f32_16x16x32_bf16 v[88:91], v[60:63], v[214:217], v[88:91]
	v_mfma_f32_16x16x32_bf16 v[92:95], v[84:87], v[214:217], v[92:95]
	v_mfma_f32_16x16x32_bf16 v[148:151], v[64:67], v[194:197], v[148:151]
	v_mfma_f32_16x16x32_bf16 v[152:155], v[104:107], v[194:197], v[152:155]
	v_mfma_f32_16x16x32_bf16 v[128:131], v[64:67], v[202:205], v[128:131]
	v_mfma_f32_16x16x32_bf16 v[132:135], v[104:107], v[202:205], v[132:135]
	v_mfma_f32_16x16x32_bf16 v[108:111], v[64:67], v[210:213], v[108:111]
	v_mfma_f32_16x16x32_bf16 v[112:115], v[104:107], v[210:213], v[112:115]
	v_mfma_f32_16x16x32_bf16 v[88:91], v[64:67], v[218:221], v[88:91]
	v_mfma_f32_16x16x32_bf16 v[92:95], v[104:107], v[218:221], v[92:95]
	v_mfma_f32_16x16x32_bf16 v[140:143], v[124:127], v[190:193], v[140:143]
	v_mfma_f32_16x16x32_bf16 v[136:139], v[156:159], v[190:193], v[136:139]
	v_mfma_f32_16x16x32_bf16 v[120:123], v[124:127], v[198:201], v[120:123]
	v_mfma_f32_16x16x32_bf16 v[116:119], v[156:159], v[198:201], v[116:119]
	v_mfma_f32_16x16x32_bf16 v[100:103], v[124:127], v[206:209], v[100:103]
	v_mfma_f32_16x16x32_bf16 v[96:99], v[156:159], v[206:209], v[96:99]
	v_mfma_f32_16x16x32_bf16 v[80:83], v[124:127], v[214:217], v[80:83]
	v_mfma_f32_16x16x32_bf16 v[76:79], v[156:159], v[214:217], v[76:79]
	v_mfma_f32_16x16x32_bf16 v[140:143], v[144:147], v[194:197], v[140:143]
	v_mfma_f32_16x16x32_bf16 v[136:139], v[180:183], v[194:197], v[136:139]
	v_mfma_f32_16x16x32_bf16 v[120:123], v[144:147], v[202:205], v[120:123]
	v_mfma_f32_16x16x32_bf16 v[116:119], v[180:183], v[202:205], v[116:119]
	v_mfma_f32_16x16x32_bf16 v[100:103], v[144:147], v[210:213], v[100:103]
	v_mfma_f32_16x16x32_bf16 v[96:99], v[180:183], v[210:213], v[96:99]
	v_mfma_f32_16x16x32_bf16 v[80:83], v[144:147], v[218:221], v[80:83]
	v_mfma_f32_16x16x32_bf16 v[76:79], v[180:183], v[218:221], v[76:79]
	s_barrier
	s_add_i32 s12, s12, s16
	v_lshl_add_u64 v[226:227], v[226:227], 0, s[82:83]
	s_mov_b32 m0, s12
	ds_read_b128 v[190:193], v188 offset:49152
	ds_read_b128 v[194:197], v188 offset:50176
	ds_read_b128 v[198:201], v188 offset:51200
	ds_read_b128 v[202:205], v188 offset:52224
	ds_read_b128 v[206:209], v188 offset:53248
	ds_read_b128 v[210:213], v188 offset:54272
	ds_read_b128 v[214:217], v188 offset:55296
	ds_read_b128 v[218:221], v188 offset:56320
	global_load_lds_dwordx4 v[226:227], off
	s_add_i32 m0, s12, 0x2000
	s_add_u32 s72, s76, 0x40080
	v_lshl_add_u64 v[226:227], v[228:229], 0, s[82:83]
	s_addc_u32 s73, s77, 0
	s_add_i32 s12, s95, s16
	global_load_lds_dwordx4 v[226:227], off
	v_lshl_add_u64 v[226:227], s[72:73], 0, v[164:165]
	s_mov_b32 m0, s12
	s_nop 0
	global_load_lds_dwordx4 v[226:227], off
	v_lshl_add_u64 v[226:227], s[72:73], 0, v[160:161]
	s_add_i32 m0, s12, 0x2000
	s_nop 0
	global_load_lds_dwordx4 v[226:227], off
	v_lshl_add_u64 v[226:227], v[230:231], 0, s[82:83]
	s_mov_b32 m0, s22
	s_nop 0
	global_load_lds_dwordx4 v[226:227], off
	v_lshl_add_u64 v[226:227], v[232:233], 0, s[82:83]
	s_mov_b32 m0, s80
	s_nop 0
	global_load_lds_dwordx4 v[226:227], off
	s_waitcnt vmcnt(8)
	s_waitcnt lgkmcnt(0)
	s_barrier
	v_mfma_f32_16x16x32_bf16 v[68:71], v[60:63], v[190:193], v[68:71]
	v_mfma_f32_16x16x32_bf16 v[72:75], v[84:87], v[190:193], v[72:75]
	v_mfma_f32_16x16x32_bf16 v[48:51], v[60:63], v[198:201], v[48:51]
	v_mfma_f32_16x16x32_bf16 v[52:55], v[84:87], v[198:201], v[52:55]
	v_mfma_f32_16x16x32_bf16 v[28:31], v[60:63], v[206:209], v[28:31]
	v_mfma_f32_16x16x32_bf16 v[32:35], v[84:87], v[206:209], v[32:35]
	v_mfma_f32_16x16x32_bf16 v[10:13], v[60:63], v[214:217], v[10:13]
	v_mfma_f32_16x16x32_bf16 v[14:17], v[84:87], v[214:217], v[14:17]
	v_mfma_f32_16x16x32_bf16 v[68:71], v[64:67], v[194:197], v[68:71]
	v_mfma_f32_16x16x32_bf16 v[72:75], v[104:107], v[194:197], v[72:75]
	v_mfma_f32_16x16x32_bf16 v[48:51], v[64:67], v[202:205], v[48:51]
	v_mfma_f32_16x16x32_bf16 v[52:55], v[104:107], v[202:205], v[52:55]
	v_mfma_f32_16x16x32_bf16 v[28:31], v[64:67], v[210:213], v[28:31]
	v_mfma_f32_16x16x32_bf16 v[32:35], v[104:107], v[210:213], v[32:35]
	v_mfma_f32_16x16x32_bf16 v[10:13], v[64:67], v[218:221], v[10:13]
	v_mfma_f32_16x16x32_bf16 v[14:17], v[104:107], v[218:221], v[14:17]
	v_mfma_f32_16x16x32_bf16 v[36:39], v[124:127], v[190:193], v[36:39]
	v_mfma_f32_16x16x32_bf16 v[64:67], v[144:147], v[194:197], v[36:39]
	v_mfma_f32_16x16x32_bf16 v[36:39], v[156:159], v[190:193], v[56:59]
	v_mfma_f32_16x16x32_bf16 v[60:63], v[180:183], v[194:197], v[36:39]
	v_mfma_f32_16x16x32_bf16 v[36:39], v[124:127], v[198:201], v[44:47]
	v_mfma_f32_16x16x32_bf16 v[44:47], v[144:147], v[202:205], v[36:39]
	v_mfma_f32_16x16x32_bf16 v[36:39], v[156:159], v[198:201], v[40:43]
	v_mfma_f32_16x16x32_bf16 v[22:25], v[124:127], v[206:209], v[22:25]
	v_mfma_f32_16x16x32_bf16 v[18:21], v[156:159], v[206:209], v[18:21]
	v_mfma_f32_16x16x32_bf16 v[2:5], v[124:127], v[214:217], v[2:5]
	v_mfma_f32_16x16x32_bf16 v[6:9], v[156:159], v[214:217], v[6:9]
	v_mfma_f32_16x16x32_bf16 v[40:43], v[180:183], v[202:205], v[36:39]
	v_mfma_f32_16x16x32_bf16 v[22:25], v[144:147], v[210:213], v[22:25]
	v_mfma_f32_16x16x32_bf16 v[18:21], v[180:183], v[210:213], v[18:21]
	v_mfma_f32_16x16x32_bf16 v[2:5], v[144:147], v[218:221], v[2:5]
	v_mfma_f32_16x16x32_bf16 v[6:9], v[180:183], v[218:221], v[6:9]
	s_barrier
	s_add_i32 s93, s93, 2
	s_add_u32 vcc_lo, vcc_lo, 0x100
	s_addc_u32 vcc_hi, vcc_hi, 0
	s_add_u32 s84, s84, 0x100
	s_addc_u32 s85, s85, 0
	s_cmp_gt_u32 s93, 13
	s_cbranch_scc0 .LBB0_111
	s_and_b64 vcc, exec, s[60:61]
	s_cbranch_vccz .LBB0_114
	s_barrier

.LBB0_207:
	s_xor_b64 s[38:39], s[38:39], -1
	s_add_u32 s90, s78, 0x20080
	s_addc_u32 s91, s79, 0
	s_add_u32 s76, s76, 0x100
	s_addc_u32 s77, s77, 0
	s_mov_b32 s78, -2
	s_add_u32 s72, s90, 0xfffe0080
	s_addc_u32 s73, s91, -1
	s_add_i32 s79, 0, 0x10000
	s_cmp_eq_u32 s78, 4
	s_cselect_b32 s95, s89, s73
	s_cselect_b32 s94, s88, s72
	s_cselect_b32 s93, s61, s77
	s_cselect_b32 s92, s60, s76
	s_add_i32 s72, 0, 0x14000
	v_add_u32_e32 v14, s79, v189
	v_add_u32_e32 v26, s72, v189
	ds_read_b128 v[2:5], v14
	ds_read_b128 v[6:9], v14 offset:1024
	ds_read_b128 v[10:13], v14 offset:2048
	ds_read_b128 v[14:17], v14 offset:3072
	ds_read_b128 v[18:21], v26
	ds_read_b128 v[22:25], v26 offset:1024
	ds_read_b128 v[192:195], v26 offset:2048
	ds_read_b128 v[196:199], v26 offset:3072
	v_lshl_add_u64 v[216:217], s[90:91], 0, v[166:167]
	s_add_i32 m0, s11, 0xc000
	ds_read_b128 v[178:181], v190
	ds_read_b128 v[182:185], v190 offset:1024
	ds_read_b128 v[200:203], v190 offset:2048
	ds_read_b128 v[204:207], v190 offset:3072
	ds_read_b128 v[208:211], v190 offset:4096
	ds_read_b128 v[212:215], v190 offset:5120
	ds_read_b128 v[226:229], v190 offset:6144
	ds_read_b128 v[230:233], v190 offset:7168
	global_load_lds_dwordx4 v[216:217], off
	v_lshl_add_u64 v[216:217], s[90:91], 0, v[176:177]
	s_add_i32 m0, s11, 0xe000
	s_nop 0
	global_load_lds_dwordx4 v[216:217], off
	s_waitcnt vmcnt(8)
	s_waitcnt lgkmcnt(0)
	s_barrier
	v_mfma_scale_f32_16x16x128_f8f6f4 v[148:151], v[2:9], v[178:185], 0, v186, v186 op_sel_hi:[0,0,0]
	v_mfma_scale_f32_16x16x128_f8f6f4 v[152:155], v[10:17], v[178:185], 0, v186, v186 op_sel_hi:[0,0,0]
	v_mfma_scale_f32_16x16x128_f8f6f4 v[124:127], v[2:9], v[200:207], 0, v186, v186 op_sel_hi:[0,0,0]
	v_mfma_scale_f32_16x16x128_f8f6f4 v[128:131], v[10:17], v[200:207], 0, v186, v186 op_sel_hi:[0,0,0]
	v_mfma_scale_f32_16x16x128_f8f6f4 v[108:111], v[2:9], v[208:215], 0, v186, v186 op_sel_hi:[0,0,0]
	v_mfma_scale_f32_16x16x128_f8f6f4 v[112:115], v[10:17], v[208:215], 0, v186, v186 op_sel_hi:[0,0,0]
	v_mfma_scale_f32_16x16x128_f8f6f4 v[92:95], v[2:9], v[226:233], 0, v186, v186 op_sel_hi:[0,0,0]
	v_mfma_scale_f32_16x16x128_f8f6f4 v[96:99], v[10:17], v[226:233], 0, v186, v186 op_sel_hi:[0,0,0]
	v_mfma_scale_f32_16x16x128_f8f6f4 v[140:143], v[18:25], v[178:185], 0, v186, v186 op_sel_hi:[0,0,0]
	v_mfma_scale_f32_16x16x128_f8f6f4 v[144:147], v[192:199], v[178:185], 0, v186, v186 op_sel_hi:[0,0,0]
	v_mfma_scale_f32_16x16x128_f8f6f4 v[132:135], v[18:25], v[200:207], 0, v186, v186 op_sel_hi:[0,0,0]
	v_mfma_scale_f32_16x16x128_f8f6f4 v[136:139], v[192:199], v[200:207], 0, v186, v186 op_sel_hi:[0,0,0]
	v_mfma_scale_f32_16x16x128_f8f6f4 v[116:119], v[18:25], v[208:215], 0, v186, v186 op_sel_hi:[0,0,0]
	v_mfma_scale_f32_16x16x128_f8f6f4 v[120:123], v[192:199], v[208:215], 0, v186, v186 op_sel_hi:[0,0,0]
	v_mfma_scale_f32_16x16x128_f8f6f4 v[100:103], v[18:25], v[226:233], 0, v186, v186 op_sel_hi:[0,0,0]
	v_mfma_scale_f32_16x16x128_f8f6f4 v[104:107], v[192:199], v[226:233], 0, v186, v186 op_sel_hi:[0,0,0]
	s_barrier
	s_add_i32 s73, s79, s8
	v_lshl_add_u64 v[178:179], s[92:93], 0, v[158:159]
	s_mov_b32 m0, s73
	ds_read_b128 v[200:203], v190 offset:16384
	ds_read_b128 v[204:207], v190 offset:17408
	ds_read_b128 v[208:211], v190 offset:18432
	ds_read_b128 v[212:215], v190 offset:19456
	ds_read_b128 v[226:229], v190 offset:20480
	ds_read_b128 v[230:233], v190 offset:21504
	ds_read_b128 v[234:237], v190 offset:22528
	ds_read_b128 v[238:241], v190 offset:23552
	global_load_lds_dwordx4 v[178:179], off
	s_add_i32 m0, s73, 0x2000
	s_add_u32 s80, s92, 0x20000
	v_lshl_add_u64 v[180:181], s[92:93], 0, v[162:163]
	s_addc_u32 s81, s93, 0
	s_add_i32 s72, s72, s8
	global_load_lds_dwordx4 v[180:181], off
	v_lshl_add_u64 v[182:183], s[80:81], 0, v[158:159]
	s_mov_b32 m0, s72
	v_lshl_add_u64 v[184:185], s[94:95], 0, v[160:161]
	global_load_lds_dwordx4 v[182:183], off
	v_lshl_add_u64 v[182:183], s[80:81], 0, v[162:163]
	s_add_i32 m0, s72, 0x2000
	s_nop 0
	global_load_lds_dwordx4 v[182:183], off
	v_lshl_add_u64 v[182:183], s[94:95], 0, v[156:157]
	s_mov_b32 m0, s11
	s_nop 0
	global_load_lds_dwordx4 v[182:183], off
	s_mov_b32 m0, s16
	s_nop 0
	global_load_lds_dwordx4 v[184:185], off
	s_waitcnt vmcnt(8)
	s_waitcnt lgkmcnt(0)
	s_barrier
	v_mfma_scale_f32_16x16x128_f8f6f4 v[76:79], v[2:9], v[200:207], 0, v186, v186 op_sel_hi:[0,0,0]
	v_mfma_scale_f32_16x16x128_f8f6f4 v[80:83], v[10:17], v[200:207], 0, v186, v186 op_sel_hi:[0,0,0]
	v_mfma_scale_f32_16x16x128_f8f6f4 v[60:63], v[2:9], v[208:215], 0, v186, v186 op_sel_hi:[0,0,0]
	v_mfma_scale_f32_16x16x128_f8f6f4 v[64:67], v[10:17], v[208:215], 0, v186, v186 op_sel_hi:[0,0,0]
	v_mfma_scale_f32_16x16x128_f8f6f4 v[44:47], v[2:9], v[226:233], 0, v186, v186 op_sel_hi:[0,0,0]
	v_mfma_scale_f32_16x16x128_f8f6f4 v[48:51], v[10:17], v[226:233], 0, v186, v186 op_sel_hi:[0,0,0]
	v_mfma_scale_f32_16x16x128_f8f6f4 v[28:31], v[2:9], v[234:241], 0, v186, v186 op_sel_hi:[0,0,0]
	v_mfma_scale_f32_16x16x128_f8f6f4 v[32:35], v[10:17], v[234:241], 0, v186, v186 op_sel_hi:[0,0,0]
	v_mfma_scale_f32_16x16x128_f8f6f4 v[84:87], v[18:25], v[200:207], 0, v186, v186 op_sel_hi:[0,0,0]
	v_mfma_scale_f32_16x16x128_f8f6f4 v[88:91], v[192:199], v[200:207], 0, v186, v186 op_sel_hi:[0,0,0]
	v_mfma_scale_f32_16x16x128_f8f6f4 v[68:71], v[18:25], v[208:215], 0, v186, v186 op_sel_hi:[0,0,0]
	v_mfma_scale_f32_16x16x128_f8f6f4 v[72:75], v[192:199], v[208:215], 0, v186, v186 op_sel_hi:[0,0,0]
	v_mfma_scale_f32_16x16x128_f8f6f4 v[52:55], v[18:25], v[226:233], 0, v186, v186 op_sel_hi:[0,0,0]
	v_mfma_scale_f32_16x16x128_f8f6f4 v[56:59], v[192:199], v[226:233], 0, v186, v186 op_sel_hi:[0,0,0]
	v_mfma_scale_f32_16x16x128_f8f6f4 v[36:39], v[18:25], v[234:241], 0, v186, v186 op_sel_hi:[0,0,0]
	v_mfma_scale_f32_16x16x128_f8f6f4 v[40:43], v[192:199], v[234:241], 0, v186, v186 op_sel_hi:[0,0,0]
	s_barrier
	s_add_i32 s79, 0, 0x18000
	s_add_i32 s72, 0, 0x1c000
	v_add_u32_e32 v2, s79, v189
	v_add_u32_e32 v22, s72, v189
	ds_read_b128 v[10:13], v2
	ds_read_b128 v[14:17], v2 offset:1024
	ds_read_b128 v[192:195], v2 offset:2048
	ds_read_b128 v[196:199], v2 offset:3072
	ds_read_b128 v[2:5], v22
	ds_read_b128 v[6:9], v22 offset:1024
	ds_read_b128 v[18:21], v22 offset:2048
	ds_read_b128 v[22:25], v22 offset:3072
	s_add_u32 s80, s94, 0x20000
	s_addc_u32 s81, s95, 0
	s_mov_b32 m0, s17
	v_lshl_add_u64 v[216:217], s[80:81], 0, v[156:157]
	ds_read_b128 v[200:203], v190 offset:32768
	ds_read_b128 v[204:207], v190 offset:33792
	ds_read_b128 v[208:211], v190 offset:34816
	ds_read_b128 v[212:215], v190 offset:35840
	ds_read_b128 v[226:229], v190 offset:36864
	ds_read_b128 v[230:233], v190 offset:37888
	ds_read_b128 v[234:237], v190 offset:38912
	ds_read_b128 v[238:241], v190 offset:39936
	global_load_lds_dwordx4 v[216:217], off
	v_lshl_add_u64 v[216:217], s[80:81], 0, v[160:161]
	s_mov_b32 m0, s22
	s_nop 0
	global_load_lds_dwordx4 v[216:217], off
	s_waitcnt vmcnt(8)
	s_waitcnt lgkmcnt(0)
	s_barrier
	v_mfma_scale_f32_16x16x128_f8f6f4 v[148:151], v[10:17], v[200:207], v[148:151], v186, v186 op_sel_hi:[0,0,0]
	v_mfma_scale_f32_16x16x128_f8f6f4 v[152:155], v[192:199], v[200:207], v[152:155], v186, v186 op_sel_hi:[0,0,0]
	v_mfma_scale_f32_16x16x128_f8f6f4 v[124:127], v[10:17], v[208:215], v[124:127], v186, v186 op_sel_hi:[0,0,0]
	v_mfma_scale_f32_16x16x128_f8f6f4 v[128:131], v[192:199], v[208:215], v[128:131], v186, v186 op_sel_hi:[0,0,0]
	v_mfma_scale_f32_16x16x128_f8f6f4 v[108:111], v[10:17], v[226:233], v[108:111], v186, v186 op_sel_hi:[0,0,0]
	v_mfma_scale_f32_16x16x128_f8f6f4 v[112:115], v[192:199], v[226:233], v[112:115], v186, v186 op_sel_hi:[0,0,0]
	v_mfma_scale_f32_16x16x128_f8f6f4 v[92:95], v[10:17], v[234:241], v[92:95], v186, v186 op_sel_hi:[0,0,0]
	v_mfma_scale_f32_16x16x128_f8f6f4 v[96:99], v[192:199], v[234:241], v[96:99], v186, v186 op_sel_hi:[0,0,0]
	v_mfma_scale_f32_16x16x128_f8f6f4 v[140:143], v[2:9], v[200:207], v[140:143], v186, v186 op_sel_hi:[0,0,0]
	v_mfma_scale_f32_16x16x128_f8f6f4 v[144:147], v[18:25], v[200:207], v[144:147], v186, v186 op_sel_hi:[0,0,0]
	v_mfma_scale_f32_16x16x128_f8f6f4 v[132:135], v[2:9], v[208:215], v[132:135], v186, v186 op_sel_hi:[0,0,0]
	v_mfma_scale_f32_16x16x128_f8f6f4 v[136:139], v[18:25], v[208:215], v[136:139], v186, v186 op_sel_hi:[0,0,0]
	v_mfma_scale_f32_16x16x128_f8f6f4 v[116:119], v[2:9], v[226:233], v[116:119], v186, v186 op_sel_hi:[0,0,0]
	v_mfma_scale_f32_16x16x128_f8f6f4 v[120:123], v[18:25], v[226:233], v[120:123], v186, v186 op_sel_hi:[0,0,0]
	v_mfma_scale_f32_16x16x128_f8f6f4 v[100:103], v[2:9], v[234:241], v[100:103], v186, v186 op_sel_hi:[0,0,0]
	v_mfma_scale_f32_16x16x128_f8f6f4 v[104:107], v[18:25], v[234:241], v[104:107], v186, v186 op_sel_hi:[0,0,0]
	s_barrier
	s_add_i32 s73, s79, s8
	v_lshl_add_u64 v[178:179], v[178:179], 0, s[82:83]
	s_mov_b32 m0, s73
	ds_read_b128 v[200:203], v190 offset:49152
	ds_read_b128 v[204:207], v190 offset:50176
	ds_read_b128 v[208:211], v190 offset:51200
	ds_read_b128 v[212:215], v190 offset:52224
	ds_read_b128 v[226:229], v190 offset:53248
	ds_read_b128 v[230:233], v190 offset:54272
	ds_read_b128 v[234:237], v190 offset:55296
	ds_read_b128 v[238:241], v190 offset:56320
	global_load_lds_dwordx4 v[178:179], off
	s_add_i32 m0, s73, 0x2000
	s_add_u32 s80, s92, 0x20080
	v_lshl_add_u64 v[178:179], v[180:181], 0, s[82:83]
	s_addc_u32 s81, s93, 0
	s_add_i32 s72, s72, s8
	global_load_lds_dwordx4 v[178:179], off
	v_lshl_add_u64 v[178:179], s[80:81], 0, v[158:159]
	s_mov_b32 m0, s72
	s_nop 0
	global_load_lds_dwordx4 v[178:179], off
	v_lshl_add_u64 v[178:179], s[80:81], 0, v[162:163]
	s_add_i32 m0, s72, 0x2000
	s_nop 0
	global_load_lds_dwordx4 v[178:179], off
	v_lshl_add_u64 v[178:179], v[182:183], 0, s[82:83]
	s_mov_b32 m0, s26
	s_nop 0
	global_load_lds_dwordx4 v[178:179], off
	v_lshl_add_u64 v[178:179], v[184:185], 0, s[82:83]
	s_mov_b32 m0, s27
	s_nop 0
	global_load_lds_dwordx4 v[178:179], off
	s_waitcnt vmcnt(8)
	s_waitcnt lgkmcnt(0)
	s_barrier
	v_mfma_scale_f32_16x16x128_f8f6f4 v[76:79], v[10:17], v[200:207], v[76:79], v186, v186 op_sel_hi:[0,0,0]
	v_mfma_scale_f32_16x16x128_f8f6f4 v[80:83], v[192:199], v[200:207], v[80:83], v186, v186 op_sel_hi:[0,0,0]
	v_mfma_scale_f32_16x16x128_f8f6f4 v[60:63], v[10:17], v[208:215], v[60:63], v186, v186 op_sel_hi:[0,0,0]
	v_mfma_scale_f32_16x16x128_f8f6f4 v[64:67], v[192:199], v[208:215], v[64:67], v186, v186 op_sel_hi:[0,0,0]
	v_mfma_scale_f32_16x16x128_f8f6f4 v[44:47], v[10:17], v[226:233], v[44:47], v186, v186 op_sel_hi:[0,0,0]
	v_mfma_scale_f32_16x16x128_f8f6f4 v[48:51], v[192:199], v[226:233], v[48:51], v186, v186 op_sel_hi:[0,0,0]
	v_mfma_scale_f32_16x16x128_f8f6f4 v[28:31], v[10:17], v[234:241], v[28:31], v186, v186 op_sel_hi:[0,0,0]
	v_mfma_scale_f32_16x16x128_f8f6f4 v[32:35], v[192:199], v[234:241], v[32:35], v186, v186 op_sel_hi:[0,0,0]
	v_mfma_scale_f32_16x16x128_f8f6f4 v[84:87], v[2:9], v[200:207], v[84:87], v186, v186 op_sel_hi:[0,0,0]
	v_mfma_scale_f32_16x16x128_f8f6f4 v[88:91], v[18:25], v[200:207], v[88:91], v186, v186 op_sel_hi:[0,0,0]
	v_mfma_scale_f32_16x16x128_f8f6f4 v[68:71], v[2:9], v[208:215], v[68:71], v186, v186 op_sel_hi:[0,0,0]
	v_mfma_scale_f32_16x16x128_f8f6f4 v[72:75], v[18:25], v[208:215], v[72:75], v186, v186 op_sel_hi:[0,0,0]
	v_mfma_scale_f32_16x16x128_f8f6f4 v[52:55], v[2:9], v[226:233], v[52:55], v186, v186 op_sel_hi:[0,0,0]
	v_mfma_scale_f32_16x16x128_f8f6f4 v[56:59], v[18:25], v[226:233], v[56:59], v186, v186 op_sel_hi:[0,0,0]
	v_mfma_scale_f32_16x16x128_f8f6f4 v[36:39], v[2:9], v[234:241], v[36:39], v186, v186 op_sel_hi:[0,0,0]
	v_mfma_scale_f32_16x16x128_f8f6f4 v[40:43], v[18:25], v[234:241], v[40:43], v186, v186 op_sel_hi:[0,0,0]
	s_barrier
	s_add_i32 s78, s78, 2
	s_add_u32 s90, s90, 0x100
	s_addc_u32 s91, s91, 0
	s_add_u32 s76, s76, 0x100
	s_addc_u32 s77, s77, 0
.LBB0_208:
	s_add_u32 s72, s90, 0xfffe0080
	s_addc_u32 s73, s91, -1
	s_add_i32 s79, 0, 0x10000
	s_cmp_eq_u32 s78, 4
	s_cselect_b32 s95, s89, s73
	s_cselect_b32 s94, s88, s72
	s_cselect_b32 s93, s61, s77
	s_cselect_b32 s92, s60, s76
	s_add_i32 s72, 0, 0x14000
	v_add_u32_e32 v14, s79, v189
	v_add_u32_e32 v26, s72, v189
	ds_read_b128 v[2:5], v14
	ds_read_b128 v[6:9], v14 offset:1024
	ds_read_b128 v[10:13], v14 offset:2048
	ds_read_b128 v[14:17], v14 offset:3072
	ds_read_b128 v[18:21], v26
	ds_read_b128 v[22:25], v26 offset:1024
	ds_read_b128 v[192:195], v26 offset:2048
	ds_read_b128 v[196:199], v26 offset:3072
	v_lshl_add_u64 v[216:217], s[90:91], 0, v[166:167]
	s_add_i32 m0, s11, 0xc000
	ds_read_b128 v[178:181], v190
	ds_read_b128 v[182:185], v190 offset:1024
	ds_read_b128 v[200:203], v190 offset:2048
	ds_read_b128 v[204:207], v190 offset:3072
	ds_read_b128 v[208:211], v190 offset:4096
	ds_read_b128 v[212:215], v190 offset:5120
	ds_read_b128 v[226:229], v190 offset:6144
	ds_read_b128 v[230:233], v190 offset:7168
	global_load_lds_dwordx4 v[216:217], off
	v_lshl_add_u64 v[216:217], s[90:91], 0, v[176:177]
	s_add_i32 m0, s11, 0xe000
	s_nop 0
	global_load_lds_dwordx4 v[216:217], off
	s_waitcnt vmcnt(8)
	s_waitcnt lgkmcnt(0)
	s_barrier
	v_mfma_scale_f32_16x16x128_f8f6f4 v[148:151], v[2:9], v[178:185], v[148:151], v186, v186 op_sel_hi:[0,0,0]
	v_mfma_scale_f32_16x16x128_f8f6f4 v[152:155], v[10:17], v[178:185], v[152:155], v186, v186 op_sel_hi:[0,0,0]
	v_mfma_scale_f32_16x16x128_f8f6f4 v[124:127], v[2:9], v[200:207], v[124:127], v186, v186 op_sel_hi:[0,0,0]
	v_mfma_scale_f32_16x16x128_f8f6f4 v[128:131], v[10:17], v[200:207], v[128:131], v186, v186 op_sel_hi:[0,0,0]
	v_mfma_scale_f32_16x16x128_f8f6f4 v[108:111], v[2:9], v[208:215], v[108:111], v186, v186 op_sel_hi:[0,0,0]
	v_mfma_scale_f32_16x16x128_f8f6f4 v[112:115], v[10:17], v[208:215], v[112:115], v186, v186 op_sel_hi:[0,0,0]
	v_mfma_scale_f32_16x16x128_f8f6f4 v[92:95], v[2:9], v[226:233], v[92:95], v186, v186 op_sel_hi:[0,0,0]
	v_mfma_scale_f32_16x16x128_f8f6f4 v[96:99], v[10:17], v[226:233], v[96:99], v186, v186 op_sel_hi:[0,0,0]
	v_mfma_scale_f32_16x16x128_f8f6f4 v[140:143], v[18:25], v[178:185], v[140:143], v186, v186 op_sel_hi:[0,0,0]
	v_mfma_scale_f32_16x16x128_f8f6f4 v[144:147], v[192:199], v[178:185], v[144:147], v186, v186 op_sel_hi:[0,0,0]
	v_mfma_scale_f32_16x16x128_f8f6f4 v[132:135], v[18:25], v[200:207], v[132:135], v186, v186 op_sel_hi:[0,0,0]
	v_mfma_scale_f32_16x16x128_f8f6f4 v[136:139], v[192:199], v[200:207], v[136:139], v186, v186 op_sel_hi:[0,0,0]
	v_mfma_scale_f32_16x16x128_f8f6f4 v[116:119], v[18:25], v[208:215], v[116:119], v186, v186 op_sel_hi:[0,0,0]
	v_mfma_scale_f32_16x16x128_f8f6f4 v[120:123], v[192:199], v[208:215], v[120:123], v186, v186 op_sel_hi:[0,0,0]
	v_mfma_scale_f32_16x16x128_f8f6f4 v[100:103], v[18:25], v[226:233], v[100:103], v186, v186 op_sel_hi:[0,0,0]
	v_mfma_scale_f32_16x16x128_f8f6f4 v[104:107], v[192:199], v[226:233], v[104:107], v186, v186 op_sel_hi:[0,0,0]
	s_barrier
	s_add_i32 s73, s79, s8
	v_lshl_add_u64 v[178:179], s[92:93], 0, v[158:159]
	s_mov_b32 m0, s73
	ds_read_b128 v[200:203], v190 offset:16384
	ds_read_b128 v[204:207], v190 offset:17408
	ds_read_b128 v[208:211], v190 offset:18432
	ds_read_b128 v[212:215], v190 offset:19456
	ds_read_b128 v[226:229], v190 offset:20480
	ds_read_b128 v[230:233], v190 offset:21504
	ds_read_b128 v[234:237], v190 offset:22528
	ds_read_b128 v[238:241], v190 offset:23552
	global_load_lds_dwordx4 v[178:179], off
	s_add_i32 m0, s73, 0x2000
	s_add_u32 s80, s92, 0x20000
	v_lshl_add_u64 v[180:181], s[92:93], 0, v[162:163]
	s_addc_u32 s81, s93, 0
	s_add_i32 s72, s72, s8
	global_load_lds_dwordx4 v[180:181], off
	v_lshl_add_u64 v[182:183], s[80:81], 0, v[158:159]
	s_mov_b32 m0, s72
	v_lshl_add_u64 v[184:185], s[94:95], 0, v[160:161]
	global_load_lds_dwordx4 v[182:183], off
	v_lshl_add_u64 v[182:183], s[80:81], 0, v[162:163]
	s_add_i32 m0, s72, 0x2000
	s_nop 0
	global_load_lds_dwordx4 v[182:183], off
	v_lshl_add_u64 v[182:183], s[94:95], 0, v[156:157]
	s_mov_b32 m0, s11
	s_nop 0
	global_load_lds_dwordx4 v[182:183], off
	s_mov_b32 m0, s16
	s_nop 0
	global_load_lds_dwordx4 v[184:185], off
	s_waitcnt vmcnt(8)
	s_waitcnt lgkmcnt(0)
	s_barrier
	v_mfma_scale_f32_16x16x128_f8f6f4 v[76:79], v[2:9], v[200:207], v[76:79], v186, v186 op_sel_hi:[0,0,0]
	v_mfma_scale_f32_16x16x128_f8f6f4 v[80:83], v[10:17], v[200:207], v[80:83], v186, v186 op_sel_hi:[0,0,0]
	v_mfma_scale_f32_16x16x128_f8f6f4 v[60:63], v[2:9], v[208:215], v[60:63], v186, v186 op_sel_hi:[0,0,0]
	v_mfma_scale_f32_16x16x128_f8f6f4 v[64:67], v[10:17], v[208:215], v[64:67], v186, v186 op_sel_hi:[0,0,0]
	v_mfma_scale_f32_16x16x128_f8f6f4 v[44:47], v[2:9], v[226:233], v[44:47], v186, v186 op_sel_hi:[0,0,0]
	v_mfma_scale_f32_16x16x128_f8f6f4 v[48:51], v[10:17], v[226:233], v[48:51], v186, v186 op_sel_hi:[0,0,0]
	v_mfma_scale_f32_16x16x128_f8f6f4 v[28:31], v[2:9], v[234:241], v[28:31], v186, v186 op_sel_hi:[0,0,0]
	v_mfma_scale_f32_16x16x128_f8f6f4 v[32:35], v[10:17], v[234:241], v[32:35], v186, v186 op_sel_hi:[0,0,0]
	v_mfma_scale_f32_16x16x128_f8f6f4 v[84:87], v[18:25], v[200:207], v[84:87], v186, v186 op_sel_hi:[0,0,0]
	v_mfma_scale_f32_16x16x128_f8f6f4 v[88:91], v[192:199], v[200:207], v[88:91], v186, v186 op_sel_hi:[0,0,0]
	v_mfma_scale_f32_16x16x128_f8f6f4 v[68:71], v[18:25], v[208:215], v[68:71], v186, v186 op_sel_hi:[0,0,0]
	v_mfma_scale_f32_16x16x128_f8f6f4 v[72:75], v[192:199], v[208:215], v[72:75], v186, v186 op_sel_hi:[0,0,0]
	v_mfma_scale_f32_16x16x128_f8f6f4 v[52:55], v[18:25], v[226:233], v[52:55], v186, v186 op_sel_hi:[0,0,0]
	v_mfma_scale_f32_16x16x128_f8f6f4 v[56:59], v[192:199], v[226:233], v[56:59], v186, v186 op_sel_hi:[0,0,0]
	v_mfma_scale_f32_16x16x128_f8f6f4 v[36:39], v[18:25], v[234:241], v[36:39], v186, v186 op_sel_hi:[0,0,0]
	v_mfma_scale_f32_16x16x128_f8f6f4 v[40:43], v[192:199], v[234:241], v[40:43], v186, v186 op_sel_hi:[0,0,0]
	s_barrier
	s_add_i32 s79, 0, 0x18000
	s_add_i32 s72, 0, 0x1c000
	v_add_u32_e32 v2, s79, v189
	v_add_u32_e32 v22, s72, v189
	ds_read_b128 v[10:13], v2
	ds_read_b128 v[14:17], v2 offset:1024
	ds_read_b128 v[192:195], v2 offset:2048
	ds_read_b128 v[196:199], v2 offset:3072
	ds_read_b128 v[2:5], v22
	ds_read_b128 v[6:9], v22 offset:1024
	ds_read_b128 v[18:21], v22 offset:2048
	ds_read_b128 v[22:25], v22 offset:3072
	s_add_u32 s80, s94, 0x20000
	s_addc_u32 s81, s95, 0
	s_mov_b32 m0, s17
	v_lshl_add_u64 v[216:217], s[80:81], 0, v[156:157]
	ds_read_b128 v[200:203], v190 offset:32768
	ds_read_b128 v[204:207], v190 offset:33792
	ds_read_b128 v[208:211], v190 offset:34816
	ds_read_b128 v[212:215], v190 offset:35840
	ds_read_b128 v[226:229], v190 offset:36864
	ds_read_b128 v[230:233], v190 offset:37888
	ds_read_b128 v[234:237], v190 offset:38912
	ds_read_b128 v[238:241], v190 offset:39936
	global_load_lds_dwordx4 v[216:217], off
	v_lshl_add_u64 v[216:217], s[80:81], 0, v[160:161]
	s_mov_b32 m0, s22
	s_nop 0
	global_load_lds_dwordx4 v[216:217], off
	s_waitcnt vmcnt(8)
	s_waitcnt lgkmcnt(0)
	s_barrier
	v_mfma_scale_f32_16x16x128_f8f6f4 v[148:151], v[10:17], v[200:207], v[148:151], v186, v186 op_sel_hi:[0,0,0]
	v_mfma_scale_f32_16x16x128_f8f6f4 v[152:155], v[192:199], v[200:207], v[152:155], v186, v186 op_sel_hi:[0,0,0]
	v_mfma_scale_f32_16x16x128_f8f6f4 v[124:127], v[10:17], v[208:215], v[124:127], v186, v186 op_sel_hi:[0,0,0]
	v_mfma_scale_f32_16x16x128_f8f6f4 v[128:131], v[192:199], v[208:215], v[128:131], v186, v186 op_sel_hi:[0,0,0]
	v_mfma_scale_f32_16x16x128_f8f6f4 v[108:111], v[10:17], v[226:233], v[108:111], v186, v186 op_sel_hi:[0,0,0]
	v_mfma_scale_f32_16x16x128_f8f6f4 v[112:115], v[192:199], v[226:233], v[112:115], v186, v186 op_sel_hi:[0,0,0]
	v_mfma_scale_f32_16x16x128_f8f6f4 v[92:95], v[10:17], v[234:241], v[92:95], v186, v186 op_sel_hi:[0,0,0]
	v_mfma_scale_f32_16x16x128_f8f6f4 v[96:99], v[192:199], v[234:241], v[96:99], v186, v186 op_sel_hi:[0,0,0]
	v_mfma_scale_f32_16x16x128_f8f6f4 v[140:143], v[2:9], v[200:207], v[140:143], v186, v186 op_sel_hi:[0,0,0]
	v_mfma_scale_f32_16x16x128_f8f6f4 v[144:147], v[18:25], v[200:207], v[144:147], v186, v186 op_sel_hi:[0,0,0]
	v_mfma_scale_f32_16x16x128_f8f6f4 v[132:135], v[2:9], v[208:215], v[132:135], v186, v186 op_sel_hi:[0,0,0]
	v_mfma_scale_f32_16x16x128_f8f6f4 v[136:139], v[18:25], v[208:215], v[136:139], v186, v186 op_sel_hi:[0,0,0]
	v_mfma_scale_f32_16x16x128_f8f6f4 v[116:119], v[2:9], v[226:233], v[116:119], v186, v186 op_sel_hi:[0,0,0]
	v_mfma_scale_f32_16x16x128_f8f6f4 v[120:123], v[18:25], v[226:233], v[120:123], v186, v186 op_sel_hi:[0,0,0]
	v_mfma_scale_f32_16x16x128_f8f6f4 v[100:103], v[2:9], v[234:241], v[100:103], v186, v186 op_sel_hi:[0,0,0]
	v_mfma_scale_f32_16x16x128_f8f6f4 v[104:107], v[18:25], v[234:241], v[104:107], v186, v186 op_sel_hi:[0,0,0]
	s_barrier
	s_add_i32 s73, s79, s8
	v_lshl_add_u64 v[178:179], v[178:179], 0, s[82:83]
	s_mov_b32 m0, s73
	ds_read_b128 v[200:203], v190 offset:49152
	ds_read_b128 v[204:207], v190 offset:50176
	ds_read_b128 v[208:211], v190 offset:51200
	ds_read_b128 v[212:215], v190 offset:52224
	ds_read_b128 v[226:229], v190 offset:53248
	ds_read_b128 v[230:233], v190 offset:54272
	ds_read_b128 v[234:237], v190 offset:55296
	ds_read_b128 v[238:241], v190 offset:56320
	global_load_lds_dwordx4 v[178:179], off
	s_add_i32 m0, s73, 0x2000
	s_add_u32 s80, s92, 0x20080
	v_lshl_add_u64 v[178:179], v[180:181], 0, s[82:83]
	s_addc_u32 s81, s93, 0
	s_add_i32 s72, s72, s8
	global_load_lds_dwordx4 v[178:179], off
	v_lshl_add_u64 v[178:179], s[80:81], 0, v[158:159]
	s_mov_b32 m0, s72
	s_nop 0
	global_load_lds_dwordx4 v[178:179], off
	v_lshl_add_u64 v[178:179], s[80:81], 0, v[162:163]
	s_add_i32 m0, s72, 0x2000
	s_nop 0
	global_load_lds_dwordx4 v[178:179], off
	v_lshl_add_u64 v[178:179], v[182:183], 0, s[82:83]
	s_mov_b32 m0, s26
	s_nop 0
	global_load_lds_dwordx4 v[178:179], off
	v_lshl_add_u64 v[178:179], v[184:185], 0, s[82:83]
	s_mov_b32 m0, s27
	s_nop 0
	global_load_lds_dwordx4 v[178:179], off
	s_waitcnt vmcnt(8)
	s_waitcnt lgkmcnt(0)
	s_barrier
	v_mfma_scale_f32_16x16x128_f8f6f4 v[76:79], v[10:17], v[200:207], v[76:79], v186, v186 op_sel_hi:[0,0,0]
	v_mfma_scale_f32_16x16x128_f8f6f4 v[80:83], v[192:199], v[200:207], v[80:83], v186, v186 op_sel_hi:[0,0,0]
	v_mfma_scale_f32_16x16x128_f8f6f4 v[60:63], v[10:17], v[208:215], v[60:63], v186, v186 op_sel_hi:[0,0,0]
	v_mfma_scale_f32_16x16x128_f8f6f4 v[64:67], v[192:199], v[208:215], v[64:67], v186, v186 op_sel_hi:[0,0,0]
	v_mfma_scale_f32_16x16x128_f8f6f4 v[44:47], v[10:17], v[226:233], v[44:47], v186, v186 op_sel_hi:[0,0,0]
	v_mfma_scale_f32_16x16x128_f8f6f4 v[48:51], v[192:199], v[226:233], v[48:51], v186, v186 op_sel_hi:[0,0,0]
	v_mfma_scale_f32_16x16x128_f8f6f4 v[28:31], v[10:17], v[234:241], v[28:31], v186, v186 op_sel_hi:[0,0,0]
	v_mfma_scale_f32_16x16x128_f8f6f4 v[32:35], v[192:199], v[234:241], v[32:35], v186, v186 op_sel_hi:[0,0,0]
	v_mfma_scale_f32_16x16x128_f8f6f4 v[84:87], v[2:9], v[200:207], v[84:87], v186, v186 op_sel_hi:[0,0,0]
	v_mfma_scale_f32_16x16x128_f8f6f4 v[88:91], v[18:25], v[200:207], v[88:91], v186, v186 op_sel_hi:[0,0,0]
	v_mfma_scale_f32_16x16x128_f8f6f4 v[68:71], v[2:9], v[208:215], v[68:71], v186, v186 op_sel_hi:[0,0,0]
	v_mfma_scale_f32_16x16x128_f8f6f4 v[72:75], v[18:25], v[208:215], v[72:75], v186, v186 op_sel_hi:[0,0,0]
	v_mfma_scale_f32_16x16x128_f8f6f4 v[52:55], v[2:9], v[226:233], v[52:55], v186, v186 op_sel_hi:[0,0,0]
	v_mfma_scale_f32_16x16x128_f8f6f4 v[56:59], v[18:25], v[226:233], v[56:59], v186, v186 op_sel_hi:[0,0,0]
	v_mfma_scale_f32_16x16x128_f8f6f4 v[36:39], v[2:9], v[234:241], v[36:39], v186, v186 op_sel_hi:[0,0,0]
	v_mfma_scale_f32_16x16x128_f8f6f4 v[40:43], v[18:25], v[234:241], v[40:43], v186, v186 op_sel_hi:[0,0,0]
	s_barrier
	s_add_i32 s78, s78, 2
	s_add_u32 s90, s90, 0x100
	s_addc_u32 s91, s91, 0
	s_add_u32 s76, s76, 0x100
	s_addc_u32 s77, s77, 0
	s_cmp_gt_u32 s78, 5
	s_cbranch_scc0 .LBB0_208
	s_and_b64 vcc, exec, s[30:31]
	s_cbranch_vccz .LBB0_211
	s_barrier

.LBB0_382:
	s_add_u32 s52, s52, 0x20080
	s_addc_u32 s53, s53, 0
	s_add_u32 s35, s20, 0x100
	s_addc_u32 s47, s21, 0
	s_mov_b32 s68, -2
	s_add_u32 s12, s52, 0xfffe0080
	s_addc_u32 s54, s53, -1
	s_add_i32 s72, 0, 0x10000
	s_cmp_eq_u32 s68, 4
	s_cselect_b32 s59, s37, s54
	s_cselect_b32 s58, s36, s12
	s_cselect_b32 s55, s21, s47
	s_cselect_b32 s54, s20, s35
	s_add_i32 s12, 0, 0x14000
	v_add_u32_e32 v14, s72, v190
	v_add_u32_e32 v26, s12, v190
	ds_read_b128 v[2:5], v14
	ds_read_b128 v[6:9], v14 offset:1024
	ds_read_b128 v[10:13], v14 offset:2048
	ds_read_b128 v[14:17], v14 offset:3072
	ds_read_b128 v[18:21], v26
	ds_read_b128 v[22:25], v26 offset:1024
	ds_read_b128 v[192:195], v26 offset:2048
	ds_read_b128 v[196:199], v26 offset:3072
	v_lshl_add_u64 v[216:217], s[52:53], 0, v[166:167]
	s_add_i32 m0, s11, 0xc000
	ds_read_b128 v[178:181], v191
	ds_read_b128 v[182:185], v191 offset:1024
	ds_read_b128 v[200:203], v191 offset:2048
	ds_read_b128 v[204:207], v191 offset:3072
	ds_read_b128 v[208:211], v191 offset:4096
	ds_read_b128 v[212:215], v191 offset:5120
	ds_read_b128 v[226:229], v191 offset:6144
	ds_read_b128 v[230:233], v191 offset:7168
	global_load_lds_dwordx4 v[216:217], off
	v_lshl_add_u64 v[216:217], s[52:53], 0, v[176:177]
	s_add_i32 m0, s11, 0xe000
	s_nop 0
	global_load_lds_dwordx4 v[216:217], off
	s_waitcnt vmcnt(8)
	s_waitcnt lgkmcnt(0)
	s_barrier
	v_mfma_scale_f32_16x16x128_f8f6f4 v[140:143], v[2:9], v[178:185], 0, v187, v187 op_sel_hi:[0,0,0]
	v_mfma_scale_f32_16x16x128_f8f6f4 v[144:147], v[10:17], v[178:185], 0, v187, v187 op_sel_hi:[0,0,0]
	v_mfma_scale_f32_16x16x128_f8f6f4 v[124:127], v[2:9], v[200:207], 0, v187, v187 op_sel_hi:[0,0,0]
	v_mfma_scale_f32_16x16x128_f8f6f4 v[128:131], v[10:17], v[200:207], 0, v187, v187 op_sel_hi:[0,0,0]
	v_mfma_scale_f32_16x16x128_f8f6f4 v[108:111], v[2:9], v[208:215], 0, v187, v187 op_sel_hi:[0,0,0]
	v_mfma_scale_f32_16x16x128_f8f6f4 v[112:115], v[10:17], v[208:215], 0, v187, v187 op_sel_hi:[0,0,0]
	v_mfma_scale_f32_16x16x128_f8f6f4 v[76:79], v[2:9], v[226:233], 0, v187, v187 op_sel_hi:[0,0,0]
	v_mfma_scale_f32_16x16x128_f8f6f4 v[84:87], v[10:17], v[226:233], 0, v187, v187 op_sel_hi:[0,0,0]
	v_mfma_scale_f32_16x16x128_f8f6f4 v[148:151], v[18:25], v[178:185], 0, v187, v187 op_sel_hi:[0,0,0]
	v_mfma_scale_f32_16x16x128_f8f6f4 v[152:155], v[192:199], v[178:185], 0, v187, v187 op_sel_hi:[0,0,0]
	v_mfma_scale_f32_16x16x128_f8f6f4 v[132:135], v[18:25], v[200:207], 0, v187, v187 op_sel_hi:[0,0,0]
	v_mfma_scale_f32_16x16x128_f8f6f4 v[136:139], v[192:199], v[200:207], 0, v187, v187 op_sel_hi:[0,0,0]
	v_mfma_scale_f32_16x16x128_f8f6f4 v[116:119], v[18:25], v[208:215], 0, v187, v187 op_sel_hi:[0,0,0]
	v_mfma_scale_f32_16x16x128_f8f6f4 v[120:123], v[192:199], v[208:215], 0, v187, v187 op_sel_hi:[0,0,0]
	v_mfma_scale_f32_16x16x128_f8f6f4 v[96:99], v[18:25], v[226:233], 0, v187, v187 op_sel_hi:[0,0,0]
	v_mfma_scale_f32_16x16x128_f8f6f4 v[104:107], v[192:199], v[226:233], 0, v187, v187 op_sel_hi:[0,0,0]
	s_barrier
	s_add_i32 s72, s72, s8
	v_lshl_add_u64 v[178:179], s[54:55], 0, v[158:159]
	s_mov_b32 m0, s72
	ds_read_b128 v[200:203], v191 offset:16384
	ds_read_b128 v[204:207], v191 offset:17408
	ds_read_b128 v[208:211], v191 offset:18432
	ds_read_b128 v[212:215], v191 offset:19456
	ds_read_b128 v[226:229], v191 offset:20480
	ds_read_b128 v[230:233], v191 offset:21504
	ds_read_b128 v[234:237], v191 offset:22528
	ds_read_b128 v[238:241], v191 offset:23552
	global_load_lds_dwordx4 v[178:179], off
	s_add_i32 m0, s72, 0x2000
	s_add_u32 s72, s54, 0x20000
	v_lshl_add_u64 v[180:181], s[54:55], 0, v[162:163]
	s_addc_u32 s73, s55, 0
	s_add_i32 s12, s12, s8
	global_load_lds_dwordx4 v[180:181], off
	v_lshl_add_u64 v[182:183], s[72:73], 0, v[158:159]
	s_mov_b32 m0, s12
	v_lshl_add_u64 v[184:185], s[58:59], 0, v[160:161]
	global_load_lds_dwordx4 v[182:183], off
	v_lshl_add_u64 v[182:183], s[72:73], 0, v[162:163]
	s_add_i32 m0, s12, 0x2000
	s_nop 0
	global_load_lds_dwordx4 v[182:183], off
	v_lshl_add_u64 v[182:183], s[58:59], 0, v[156:157]
	s_mov_b32 m0, s11
	s_nop 0
	global_load_lds_dwordx4 v[182:183], off
	s_mov_b32 m0, s16
	s_nop 0
	global_load_lds_dwordx4 v[184:185], off
	s_waitcnt vmcnt(8)
	s_waitcnt lgkmcnt(0)
	s_barrier
	v_mfma_scale_f32_16x16x128_f8f6f4 v[80:83], v[2:9], v[200:207], 0, v187, v187 op_sel_hi:[0,0,0]
	v_mfma_scale_f32_16x16x128_f8f6f4 v[88:91], v[10:17], v[200:207], 0, v187, v187 op_sel_hi:[0,0,0]
	v_mfma_scale_f32_16x16x128_f8f6f4 v[60:63], v[2:9], v[208:215], 0, v187, v187 op_sel_hi:[0,0,0]
	v_mfma_scale_f32_16x16x128_f8f6f4 v[64:67], v[10:17], v[208:215], 0, v187, v187 op_sel_hi:[0,0,0]
	v_mfma_scale_f32_16x16x128_f8f6f4 v[44:47], v[2:9], v[226:233], 0, v187, v187 op_sel_hi:[0,0,0]
	v_mfma_scale_f32_16x16x128_f8f6f4 v[48:51], v[10:17], v[226:233], 0, v187, v187 op_sel_hi:[0,0,0]
	v_mfma_scale_f32_16x16x128_f8f6f4 v[28:31], v[2:9], v[234:241], 0, v187, v187 op_sel_hi:[0,0,0]
	v_mfma_scale_f32_16x16x128_f8f6f4 v[32:35], v[10:17], v[234:241], 0, v187, v187 op_sel_hi:[0,0,0]
	v_mfma_scale_f32_16x16x128_f8f6f4 v[92:95], v[18:25], v[200:207], 0, v187, v187 op_sel_hi:[0,0,0]
	v_mfma_scale_f32_16x16x128_f8f6f4 v[100:103], v[192:199], v[200:207], 0, v187, v187 op_sel_hi:[0,0,0]
	v_mfma_scale_f32_16x16x128_f8f6f4 v[68:71], v[18:25], v[208:215], 0, v187, v187 op_sel_hi:[0,0,0]
	v_mfma_scale_f32_16x16x128_f8f6f4 v[72:75], v[192:199], v[208:215], 0, v187, v187 op_sel_hi:[0,0,0]
	v_mfma_scale_f32_16x16x128_f8f6f4 v[52:55], v[18:25], v[226:233], 0, v187, v187 op_sel_hi:[0,0,0]
	v_mfma_scale_f32_16x16x128_f8f6f4 v[56:59], v[192:199], v[226:233], 0, v187, v187 op_sel_hi:[0,0,0]
	v_mfma_scale_f32_16x16x128_f8f6f4 v[36:39], v[18:25], v[234:241], 0, v187, v187 op_sel_hi:[0,0,0]
	v_mfma_scale_f32_16x16x128_f8f6f4 v[40:43], v[192:199], v[234:241], 0, v187, v187 op_sel_hi:[0,0,0]
	s_barrier
	s_add_i32 s74, 0, 0x18000
	s_add_i32 s12, 0, 0x1c000
	v_add_u32_e32 v2, s74, v190
	v_add_u32_e32 v22, s12, v190
	ds_read_b128 v[10:13], v2
	ds_read_b128 v[14:17], v2 offset:1024
	ds_read_b128 v[192:195], v2 offset:2048
	ds_read_b128 v[196:199], v2 offset:3072
	ds_read_b128 v[2:5], v22
	ds_read_b128 v[6:9], v22 offset:1024
	ds_read_b128 v[18:21], v22 offset:2048
	ds_read_b128 v[22:25], v22 offset:3072
	s_add_u32 s58, s58, 0x20000
	s_addc_u32 s59, s59, 0
	s_mov_b32 m0, s17
	v_lshl_add_u64 v[216:217], s[58:59], 0, v[156:157]
	ds_read_b128 v[200:203], v191 offset:32768
	ds_read_b128 v[204:207], v191 offset:33792
	ds_read_b128 v[208:211], v191 offset:34816
	ds_read_b128 v[212:215], v191 offset:35840
	ds_read_b128 v[226:229], v191 offset:36864
	ds_read_b128 v[230:233], v191 offset:37888
	ds_read_b128 v[234:237], v191 offset:38912
	ds_read_b128 v[238:241], v191 offset:39936
	global_load_lds_dwordx4 v[216:217], off
	v_lshl_add_u64 v[216:217], s[58:59], 0, v[160:161]
	s_mov_b32 m0, s22
	s_nop 0
	global_load_lds_dwordx4 v[216:217], off
	s_waitcnt vmcnt(8)
	s_waitcnt lgkmcnt(0)
	s_barrier
	v_mfma_scale_f32_16x16x128_f8f6f4 v[140:143], v[10:17], v[200:207], v[140:143], v187, v187 op_sel_hi:[0,0,0]
	v_mfma_scale_f32_16x16x128_f8f6f4 v[144:147], v[192:199], v[200:207], v[144:147], v187, v187 op_sel_hi:[0,0,0]
	v_mfma_scale_f32_16x16x128_f8f6f4 v[124:127], v[10:17], v[208:215], v[124:127], v187, v187 op_sel_hi:[0,0,0]
	v_mfma_scale_f32_16x16x128_f8f6f4 v[128:131], v[192:199], v[208:215], v[128:131], v187, v187 op_sel_hi:[0,0,0]
	v_mfma_scale_f32_16x16x128_f8f6f4 v[108:111], v[10:17], v[226:233], v[108:111], v187, v187 op_sel_hi:[0,0,0]
	v_mfma_scale_f32_16x16x128_f8f6f4 v[112:115], v[192:199], v[226:233], v[112:115], v187, v187 op_sel_hi:[0,0,0]
	v_mfma_scale_f32_16x16x128_f8f6f4 v[76:79], v[10:17], v[234:241], v[76:79], v187, v187 op_sel_hi:[0,0,0]
	v_mfma_scale_f32_16x16x128_f8f6f4 v[84:87], v[192:199], v[234:241], v[84:87], v187, v187 op_sel_hi:[0,0,0]
	v_mfma_scale_f32_16x16x128_f8f6f4 v[148:151], v[2:9], v[200:207], v[148:151], v187, v187 op_sel_hi:[0,0,0]
	v_mfma_scale_f32_16x16x128_f8f6f4 v[152:155], v[18:25], v[200:207], v[152:155], v187, v187 op_sel_hi:[0,0,0]
	v_mfma_scale_f32_16x16x128_f8f6f4 v[132:135], v[2:9], v[208:215], v[132:135], v187, v187 op_sel_hi:[0,0,0]
	v_mfma_scale_f32_16x16x128_f8f6f4 v[136:139], v[18:25], v[208:215], v[136:139], v187, v187 op_sel_hi:[0,0,0]
	v_mfma_scale_f32_16x16x128_f8f6f4 v[116:119], v[2:9], v[226:233], v[116:119], v187, v187 op_sel_hi:[0,0,0]
	v_mfma_scale_f32_16x16x128_f8f6f4 v[120:123], v[18:25], v[226:233], v[120:123], v187, v187 op_sel_hi:[0,0,0]
	v_mfma_scale_f32_16x16x128_f8f6f4 v[96:99], v[2:9], v[234:241], v[96:99], v187, v187 op_sel_hi:[0,0,0]
	v_mfma_scale_f32_16x16x128_f8f6f4 v[104:107], v[18:25], v[234:241], v[104:107], v187, v187 op_sel_hi:[0,0,0]
	s_barrier
	s_add_i32 s58, s74, s8
	v_lshl_add_u64 v[178:179], v[178:179], 0, s[82:83]
	s_mov_b32 m0, s58
	ds_read_b128 v[200:203], v191 offset:49152
	ds_read_b128 v[204:207], v191 offset:50176
	ds_read_b128 v[208:211], v191 offset:51200
	ds_read_b128 v[212:215], v191 offset:52224
	ds_read_b128 v[226:229], v191 offset:53248
	ds_read_b128 v[230:233], v191 offset:54272
	ds_read_b128 v[234:237], v191 offset:55296
	ds_read_b128 v[238:241], v191 offset:56320
	global_load_lds_dwordx4 v[178:179], off
	s_add_i32 m0, s58, 0x2000
	s_add_u32 s54, s54, 0x20080
	v_lshl_add_u64 v[178:179], v[180:181], 0, s[82:83]
	s_addc_u32 s55, s55, 0
	s_add_i32 s12, s12, s8
	global_load_lds_dwordx4 v[178:179], off
	v_lshl_add_u64 v[178:179], s[54:55], 0, v[158:159]
	s_mov_b32 m0, s12
	s_nop 0
	global_load_lds_dwordx4 v[178:179], off
	v_lshl_add_u64 v[178:179], s[54:55], 0, v[162:163]
	s_add_i32 m0, s12, 0x2000
	s_nop 0
	global_load_lds_dwordx4 v[178:179], off
	v_lshl_add_u64 v[178:179], v[182:183], 0, s[82:83]
	s_mov_b32 m0, s23
	s_nop 0
	global_load_lds_dwordx4 v[178:179], off
	v_lshl_add_u64 v[178:179], v[184:185], 0, s[82:83]
	s_mov_b32 m0, s26
	s_nop 0
	global_load_lds_dwordx4 v[178:179], off
	s_waitcnt vmcnt(8)
	s_waitcnt lgkmcnt(0)
	s_barrier
	v_mfma_scale_f32_16x16x128_f8f6f4 v[80:83], v[10:17], v[200:207], v[80:83], v187, v187 op_sel_hi:[0,0,0]
	v_mfma_scale_f32_16x16x128_f8f6f4 v[88:91], v[192:199], v[200:207], v[88:91], v187, v187 op_sel_hi:[0,0,0]
	v_mfma_scale_f32_16x16x128_f8f6f4 v[60:63], v[10:17], v[208:215], v[60:63], v187, v187 op_sel_hi:[0,0,0]
	v_mfma_scale_f32_16x16x128_f8f6f4 v[64:67], v[192:199], v[208:215], v[64:67], v187, v187 op_sel_hi:[0,0,0]
	v_mfma_scale_f32_16x16x128_f8f6f4 v[44:47], v[10:17], v[226:233], v[44:47], v187, v187 op_sel_hi:[0,0,0]
	v_mfma_scale_f32_16x16x128_f8f6f4 v[48:51], v[192:199], v[226:233], v[48:51], v187, v187 op_sel_hi:[0,0,0]
	v_mfma_scale_f32_16x16x128_f8f6f4 v[28:31], v[10:17], v[234:241], v[28:31], v187, v187 op_sel_hi:[0,0,0]
	v_mfma_scale_f32_16x16x128_f8f6f4 v[32:35], v[192:199], v[234:241], v[32:35], v187, v187 op_sel_hi:[0,0,0]
	v_mfma_scale_f32_16x16x128_f8f6f4 v[92:95], v[2:9], v[200:207], v[92:95], v187, v187 op_sel_hi:[0,0,0]
	v_mfma_scale_f32_16x16x128_f8f6f4 v[100:103], v[18:25], v[200:207], v[100:103], v187, v187 op_sel_hi:[0,0,0]
	v_mfma_scale_f32_16x16x128_f8f6f4 v[68:71], v[2:9], v[208:215], v[68:71], v187, v187 op_sel_hi:[0,0,0]
	v_mfma_scale_f32_16x16x128_f8f6f4 v[72:75], v[18:25], v[208:215], v[72:75], v187, v187 op_sel_hi:[0,0,0]
	v_mfma_scale_f32_16x16x128_f8f6f4 v[52:55], v[2:9], v[226:233], v[52:55], v187, v187 op_sel_hi:[0,0,0]
	v_mfma_scale_f32_16x16x128_f8f6f4 v[56:59], v[18:25], v[226:233], v[56:59], v187, v187 op_sel_hi:[0,0,0]
	v_mfma_scale_f32_16x16x128_f8f6f4 v[36:39], v[2:9], v[234:241], v[36:39], v187, v187 op_sel_hi:[0,0,0]
	v_mfma_scale_f32_16x16x128_f8f6f4 v[40:43], v[18:25], v[234:241], v[40:43], v187, v187 op_sel_hi:[0,0,0]
	s_barrier
	s_add_i32 s68, s68, 2
	s_add_u32 s52, s52, 0x100
	s_addc_u32 s53, s53, 0
	s_add_u32 s35, s35, 0x100
	s_addc_u32 s47, s47, 0
.LBB0_383:
	s_add_u32 s12, s52, 0xfffe0080
	s_addc_u32 s54, s53, -1
	s_add_i32 s72, 0, 0x10000
	s_cmp_eq_u32 s68, 4
	s_cselect_b32 s59, s37, s54
	s_cselect_b32 s58, s36, s12
	s_cselect_b32 s55, s21, s47
	s_cselect_b32 s54, s20, s35
	s_add_i32 s12, 0, 0x14000
	v_add_u32_e32 v14, s72, v190
	v_add_u32_e32 v26, s12, v190
	ds_read_b128 v[2:5], v14
	ds_read_b128 v[6:9], v14 offset:1024
	ds_read_b128 v[10:13], v14 offset:2048
	ds_read_b128 v[14:17], v14 offset:3072
	ds_read_b128 v[18:21], v26
	ds_read_b128 v[22:25], v26 offset:1024
	ds_read_b128 v[192:195], v26 offset:2048
	ds_read_b128 v[196:199], v26 offset:3072
	v_lshl_add_u64 v[216:217], s[52:53], 0, v[166:167]
	s_add_i32 m0, s11, 0xc000
	ds_read_b128 v[178:181], v191
	ds_read_b128 v[182:185], v191 offset:1024
	ds_read_b128 v[200:203], v191 offset:2048
	ds_read_b128 v[204:207], v191 offset:3072
	ds_read_b128 v[208:211], v191 offset:4096
	ds_read_b128 v[212:215], v191 offset:5120
	ds_read_b128 v[226:229], v191 offset:6144
	ds_read_b128 v[230:233], v191 offset:7168
	global_load_lds_dwordx4 v[216:217], off
	v_lshl_add_u64 v[216:217], s[52:53], 0, v[176:177]
	s_add_i32 m0, s11, 0xe000
	s_nop 0
	global_load_lds_dwordx4 v[216:217], off
	s_waitcnt vmcnt(8)
	s_waitcnt lgkmcnt(0)
	s_barrier
	v_mfma_scale_f32_16x16x128_f8f6f4 v[140:143], v[2:9], v[178:185], v[140:143], v187, v187 op_sel_hi:[0,0,0]
	v_mfma_scale_f32_16x16x128_f8f6f4 v[144:147], v[10:17], v[178:185], v[144:147], v187, v187 op_sel_hi:[0,0,0]
	v_mfma_scale_f32_16x16x128_f8f6f4 v[124:127], v[2:9], v[200:207], v[124:127], v187, v187 op_sel_hi:[0,0,0]
	v_mfma_scale_f32_16x16x128_f8f6f4 v[128:131], v[10:17], v[200:207], v[128:131], v187, v187 op_sel_hi:[0,0,0]
	v_mfma_scale_f32_16x16x128_f8f6f4 v[108:111], v[2:9], v[208:215], v[108:111], v187, v187 op_sel_hi:[0,0,0]
	v_mfma_scale_f32_16x16x128_f8f6f4 v[112:115], v[10:17], v[208:215], v[112:115], v187, v187 op_sel_hi:[0,0,0]
	v_mfma_scale_f32_16x16x128_f8f6f4 v[76:79], v[2:9], v[226:233], v[76:79], v187, v187 op_sel_hi:[0,0,0]
	v_mfma_scale_f32_16x16x128_f8f6f4 v[84:87], v[10:17], v[226:233], v[84:87], v187, v187 op_sel_hi:[0,0,0]
	v_mfma_scale_f32_16x16x128_f8f6f4 v[148:151], v[18:25], v[178:185], v[148:151], v187, v187 op_sel_hi:[0,0,0]
	v_mfma_scale_f32_16x16x128_f8f6f4 v[152:155], v[192:199], v[178:185], v[152:155], v187, v187 op_sel_hi:[0,0,0]
	v_mfma_scale_f32_16x16x128_f8f6f4 v[132:135], v[18:25], v[200:207], v[132:135], v187, v187 op_sel_hi:[0,0,0]
	v_mfma_scale_f32_16x16x128_f8f6f4 v[136:139], v[192:199], v[200:207], v[136:139], v187, v187 op_sel_hi:[0,0,0]
	v_mfma_scale_f32_16x16x128_f8f6f4 v[116:119], v[18:25], v[208:215], v[116:119], v187, v187 op_sel_hi:[0,0,0]
	v_mfma_scale_f32_16x16x128_f8f6f4 v[120:123], v[192:199], v[208:215], v[120:123], v187, v187 op_sel_hi:[0,0,0]
	v_mfma_scale_f32_16x16x128_f8f6f4 v[96:99], v[18:25], v[226:233], v[96:99], v187, v187 op_sel_hi:[0,0,0]
	v_mfma_scale_f32_16x16x128_f8f6f4 v[104:107], v[192:199], v[226:233], v[104:107], v187, v187 op_sel_hi:[0,0,0]
	s_barrier
	s_add_i32 s72, s72, s8
	v_lshl_add_u64 v[178:179], s[54:55], 0, v[158:159]
	s_mov_b32 m0, s72
	ds_read_b128 v[200:203], v191 offset:16384
	ds_read_b128 v[204:207], v191 offset:17408
	ds_read_b128 v[208:211], v191 offset:18432
	ds_read_b128 v[212:215], v191 offset:19456
	ds_read_b128 v[226:229], v191 offset:20480
	ds_read_b128 v[230:233], v191 offset:21504
	ds_read_b128 v[234:237], v191 offset:22528
	ds_read_b128 v[238:241], v191 offset:23552
	global_load_lds_dwordx4 v[178:179], off
	s_add_i32 m0, s72, 0x2000
	s_add_u32 s72, s54, 0x20000
	v_lshl_add_u64 v[180:181], s[54:55], 0, v[162:163]
	s_addc_u32 s73, s55, 0
	s_add_i32 s12, s12, s8
	global_load_lds_dwordx4 v[180:181], off
	v_lshl_add_u64 v[182:183], s[72:73], 0, v[158:159]
	s_mov_b32 m0, s12
	v_lshl_add_u64 v[184:185], s[58:59], 0, v[160:161]
	global_load_lds_dwordx4 v[182:183], off
	v_lshl_add_u64 v[182:183], s[72:73], 0, v[162:163]
	s_add_i32 m0, s12, 0x2000
	s_nop 0
	global_load_lds_dwordx4 v[182:183], off
	v_lshl_add_u64 v[182:183], s[58:59], 0, v[156:157]
	s_mov_b32 m0, s11
	s_nop 0
	global_load_lds_dwordx4 v[182:183], off
	s_mov_b32 m0, s16
	s_nop 0
	global_load_lds_dwordx4 v[184:185], off
	s_waitcnt vmcnt(8)
	s_waitcnt lgkmcnt(0)
	s_barrier
	v_mfma_scale_f32_16x16x128_f8f6f4 v[80:83], v[2:9], v[200:207], v[80:83], v187, v187 op_sel_hi:[0,0,0]
	v_mfma_scale_f32_16x16x128_f8f6f4 v[88:91], v[10:17], v[200:207], v[88:91], v187, v187 op_sel_hi:[0,0,0]
	v_mfma_scale_f32_16x16x128_f8f6f4 v[60:63], v[2:9], v[208:215], v[60:63], v187, v187 op_sel_hi:[0,0,0]
	v_mfma_scale_f32_16x16x128_f8f6f4 v[64:67], v[10:17], v[208:215], v[64:67], v187, v187 op_sel_hi:[0,0,0]
	v_mfma_scale_f32_16x16x128_f8f6f4 v[44:47], v[2:9], v[226:233], v[44:47], v187, v187 op_sel_hi:[0,0,0]
	v_mfma_scale_f32_16x16x128_f8f6f4 v[48:51], v[10:17], v[226:233], v[48:51], v187, v187 op_sel_hi:[0,0,0]
	v_mfma_scale_f32_16x16x128_f8f6f4 v[28:31], v[2:9], v[234:241], v[28:31], v187, v187 op_sel_hi:[0,0,0]
	v_mfma_scale_f32_16x16x128_f8f6f4 v[32:35], v[10:17], v[234:241], v[32:35], v187, v187 op_sel_hi:[0,0,0]
	v_mfma_scale_f32_16x16x128_f8f6f4 v[92:95], v[18:25], v[200:207], v[92:95], v187, v187 op_sel_hi:[0,0,0]
	v_mfma_scale_f32_16x16x128_f8f6f4 v[100:103], v[192:199], v[200:207], v[100:103], v187, v187 op_sel_hi:[0,0,0]
	v_mfma_scale_f32_16x16x128_f8f6f4 v[68:71], v[18:25], v[208:215], v[68:71], v187, v187 op_sel_hi:[0,0,0]
	v_mfma_scale_f32_16x16x128_f8f6f4 v[72:75], v[192:199], v[208:215], v[72:75], v187, v187 op_sel_hi:[0,0,0]
	v_mfma_scale_f32_16x16x128_f8f6f4 v[52:55], v[18:25], v[226:233], v[52:55], v187, v187 op_sel_hi:[0,0,0]
	v_mfma_scale_f32_16x16x128_f8f6f4 v[56:59], v[192:199], v[226:233], v[56:59], v187, v187 op_sel_hi:[0,0,0]
	v_mfma_scale_f32_16x16x128_f8f6f4 v[36:39], v[18:25], v[234:241], v[36:39], v187, v187 op_sel_hi:[0,0,0]
	v_mfma_scale_f32_16x16x128_f8f6f4 v[40:43], v[192:199], v[234:241], v[40:43], v187, v187 op_sel_hi:[0,0,0]
	s_barrier
	s_add_i32 s74, 0, 0x18000
	s_add_i32 s12, 0, 0x1c000
	v_add_u32_e32 v2, s74, v190
	v_add_u32_e32 v22, s12, v190
	ds_read_b128 v[10:13], v2
	ds_read_b128 v[14:17], v2 offset:1024
	ds_read_b128 v[192:195], v2 offset:2048
	ds_read_b128 v[196:199], v2 offset:3072
	ds_read_b128 v[2:5], v22
	ds_read_b128 v[6:9], v22 offset:1024
	ds_read_b128 v[18:21], v22 offset:2048
	ds_read_b128 v[22:25], v22 offset:3072
	s_add_u32 s58, s58, 0x20000
	s_addc_u32 s59, s59, 0
	s_mov_b32 m0, s17
	v_lshl_add_u64 v[216:217], s[58:59], 0, v[156:157]
	ds_read_b128 v[200:203], v191 offset:32768
	ds_read_b128 v[204:207], v191 offset:33792
	ds_read_b128 v[208:211], v191 offset:34816
	ds_read_b128 v[212:215], v191 offset:35840
	ds_read_b128 v[226:229], v191 offset:36864
	ds_read_b128 v[230:233], v191 offset:37888
	ds_read_b128 v[234:237], v191 offset:38912
	ds_read_b128 v[238:241], v191 offset:39936
	global_load_lds_dwordx4 v[216:217], off
	v_lshl_add_u64 v[216:217], s[58:59], 0, v[160:161]
	s_mov_b32 m0, s22
	s_nop 0
	global_load_lds_dwordx4 v[216:217], off
	s_waitcnt vmcnt(8)
	s_waitcnt lgkmcnt(0)
	s_barrier
	v_mfma_scale_f32_16x16x128_f8f6f4 v[140:143], v[10:17], v[200:207], v[140:143], v187, v187 op_sel_hi:[0,0,0]
	v_mfma_scale_f32_16x16x128_f8f6f4 v[144:147], v[192:199], v[200:207], v[144:147], v187, v187 op_sel_hi:[0,0,0]
	v_mfma_scale_f32_16x16x128_f8f6f4 v[124:127], v[10:17], v[208:215], v[124:127], v187, v187 op_sel_hi:[0,0,0]
	v_mfma_scale_f32_16x16x128_f8f6f4 v[128:131], v[192:199], v[208:215], v[128:131], v187, v187 op_sel_hi:[0,0,0]
	v_mfma_scale_f32_16x16x128_f8f6f4 v[108:111], v[10:17], v[226:233], v[108:111], v187, v187 op_sel_hi:[0,0,0]
	v_mfma_scale_f32_16x16x128_f8f6f4 v[112:115], v[192:199], v[226:233], v[112:115], v187, v187 op_sel_hi:[0,0,0]
	v_mfma_scale_f32_16x16x128_f8f6f4 v[76:79], v[10:17], v[234:241], v[76:79], v187, v187 op_sel_hi:[0,0,0]
	v_mfma_scale_f32_16x16x128_f8f6f4 v[84:87], v[192:199], v[234:241], v[84:87], v187, v187 op_sel_hi:[0,0,0]
	v_mfma_scale_f32_16x16x128_f8f6f4 v[148:151], v[2:9], v[200:207], v[148:151], v187, v187 op_sel_hi:[0,0,0]
	v_mfma_scale_f32_16x16x128_f8f6f4 v[152:155], v[18:25], v[200:207], v[152:155], v187, v187 op_sel_hi:[0,0,0]
	v_mfma_scale_f32_16x16x128_f8f6f4 v[132:135], v[2:9], v[208:215], v[132:135], v187, v187 op_sel_hi:[0,0,0]
	v_mfma_scale_f32_16x16x128_f8f6f4 v[136:139], v[18:25], v[208:215], v[136:139], v187, v187 op_sel_hi:[0,0,0]
	v_mfma_scale_f32_16x16x128_f8f6f4 v[116:119], v[2:9], v[226:233], v[116:119], v187, v187 op_sel_hi:[0,0,0]
	v_mfma_scale_f32_16x16x128_f8f6f4 v[120:123], v[18:25], v[226:233], v[120:123], v187, v187 op_sel_hi:[0,0,0]
	v_mfma_scale_f32_16x16x128_f8f6f4 v[96:99], v[2:9], v[234:241], v[96:99], v187, v187 op_sel_hi:[0,0,0]
	v_mfma_scale_f32_16x16x128_f8f6f4 v[104:107], v[18:25], v[234:241], v[104:107], v187, v187 op_sel_hi:[0,0,0]
	s_barrier
	s_add_i32 s58, s74, s8
	v_lshl_add_u64 v[178:179], v[178:179], 0, s[82:83]
	s_mov_b32 m0, s58
	ds_read_b128 v[200:203], v191 offset:49152
	ds_read_b128 v[204:207], v191 offset:50176
	ds_read_b128 v[208:211], v191 offset:51200
	ds_read_b128 v[212:215], v191 offset:52224
	ds_read_b128 v[226:229], v191 offset:53248
	ds_read_b128 v[230:233], v191 offset:54272
	ds_read_b128 v[234:237], v191 offset:55296
	ds_read_b128 v[238:241], v191 offset:56320
	global_load_lds_dwordx4 v[178:179], off
	s_add_i32 m0, s58, 0x2000
	s_add_u32 s54, s54, 0x20080
	v_lshl_add_u64 v[178:179], v[180:181], 0, s[82:83]
	s_addc_u32 s55, s55, 0
	s_add_i32 s12, s12, s8
	global_load_lds_dwordx4 v[178:179], off
	v_lshl_add_u64 v[178:179], s[54:55], 0, v[158:159]
	s_mov_b32 m0, s12
	s_nop 0
	global_load_lds_dwordx4 v[178:179], off
	v_lshl_add_u64 v[178:179], s[54:55], 0, v[162:163]
	s_add_i32 m0, s12, 0x2000
	s_nop 0
	global_load_lds_dwordx4 v[178:179], off
	v_lshl_add_u64 v[178:179], v[182:183], 0, s[82:83]
	s_mov_b32 m0, s23
	s_nop 0
	global_load_lds_dwordx4 v[178:179], off
	v_lshl_add_u64 v[178:179], v[184:185], 0, s[82:83]
	s_mov_b32 m0, s26
	s_nop 0
	global_load_lds_dwordx4 v[178:179], off
	s_waitcnt vmcnt(8)
	s_waitcnt lgkmcnt(0)
	s_barrier
	v_mfma_scale_f32_16x16x128_f8f6f4 v[80:83], v[10:17], v[200:207], v[80:83], v187, v187 op_sel_hi:[0,0,0]
	v_mfma_scale_f32_16x16x128_f8f6f4 v[88:91], v[192:199], v[200:207], v[88:91], v187, v187 op_sel_hi:[0,0,0]
	v_mfma_scale_f32_16x16x128_f8f6f4 v[60:63], v[10:17], v[208:215], v[60:63], v187, v187 op_sel_hi:[0,0,0]
	v_mfma_scale_f32_16x16x128_f8f6f4 v[64:67], v[192:199], v[208:215], v[64:67], v187, v187 op_sel_hi:[0,0,0]
	v_mfma_scale_f32_16x16x128_f8f6f4 v[44:47], v[10:17], v[226:233], v[44:47], v187, v187 op_sel_hi:[0,0,0]
	v_mfma_scale_f32_16x16x128_f8f6f4 v[48:51], v[192:199], v[226:233], v[48:51], v187, v187 op_sel_hi:[0,0,0]
	v_mfma_scale_f32_16x16x128_f8f6f4 v[28:31], v[10:17], v[234:241], v[28:31], v187, v187 op_sel_hi:[0,0,0]
	v_mfma_scale_f32_16x16x128_f8f6f4 v[32:35], v[192:199], v[234:241], v[32:35], v187, v187 op_sel_hi:[0,0,0]
	v_mfma_scale_f32_16x16x128_f8f6f4 v[92:95], v[2:9], v[200:207], v[92:95], v187, v187 op_sel_hi:[0,0,0]
	v_mfma_scale_f32_16x16x128_f8f6f4 v[100:103], v[18:25], v[200:207], v[100:103], v187, v187 op_sel_hi:[0,0,0]
	v_mfma_scale_f32_16x16x128_f8f6f4 v[68:71], v[2:9], v[208:215], v[68:71], v187, v187 op_sel_hi:[0,0,0]
	v_mfma_scale_f32_16x16x128_f8f6f4 v[72:75], v[18:25], v[208:215], v[72:75], v187, v187 op_sel_hi:[0,0,0]
	v_mfma_scale_f32_16x16x128_f8f6f4 v[52:55], v[2:9], v[226:233], v[52:55], v187, v187 op_sel_hi:[0,0,0]
	v_mfma_scale_f32_16x16x128_f8f6f4 v[56:59], v[18:25], v[226:233], v[56:59], v187, v187 op_sel_hi:[0,0,0]
	v_mfma_scale_f32_16x16x128_f8f6f4 v[36:39], v[2:9], v[234:241], v[36:39], v187, v187 op_sel_hi:[0,0,0]
	v_mfma_scale_f32_16x16x128_f8f6f4 v[40:43], v[18:25], v[234:241], v[40:43], v187, v187 op_sel_hi:[0,0,0]
	s_barrier
	s_add_i32 s68, s68, 2
	s_add_u32 s52, s52, 0x100
	s_addc_u32 s53, s53, 0
	s_add_u32 s35, s35, 0x100
	s_addc_u32 s47, s47, 0
	s_cmp_gt_u32 s68, 5
	s_cbranch_scc0 .LBB0_383
	s_and_b64 vcc, exec, s[30:31]
	s_cbranch_vccz .LBB0_386
	s_barrier

.LBB0_492:
	s_add_i32 s12, s20, 0xf2de0080
	s_cmp_lg_u32 s36, 4
	s_cselect_b32 s12, s12, 0
	s_add_u32 s30, s84, s12
	s_addc_u32 s31, s85, 0
	s_add_i32 s37, 0, 0x10000
	s_add_u32 s28, s0, s12
	s_addc_u32 s29, s1, 0
	s_add_i32 s12, 0, 0x14000
	v_add_u32_e32 v14, s37, v186
	v_add_u32_e32 v166, s12, v186
	ds_read_b128 v[2:5], v14
	ds_read_b128 v[6:9], v14 offset:1024
	ds_read_b128 v[10:13], v14 offset:2048
	ds_read_b128 v[14:17], v14 offset:3072
	ds_read_b128 v[18:21], v166
	ds_read_b128 v[22:25], v166 offset:1024
	ds_read_b128 v[188:191], v166 offset:2048
	ds_read_b128 v[192:195], v166 offset:3072
	v_lshl_add_u64 v[166:167], v[162:163], 0, s[20:21]
	s_add_i32 m0, s17, 0xc000
	ds_read_b128 v[196:199], v187
	ds_read_b128 v[200:203], v187 offset:1024
	ds_read_b128 v[204:207], v187 offset:2048
	ds_read_b128 v[208:211], v187 offset:3072
	ds_read_b128 v[212:215], v187 offset:4096
	ds_read_b128 v[216:219], v187 offset:5120
	ds_read_b128 v[226:229], v187 offset:6144
	ds_read_b128 v[230:233], v187 offset:7168
	global_load_lds_dwordx4 v[166:167], off
	v_lshl_add_u64 v[166:167], v[164:165], 0, s[20:21]
	s_add_i32 m0, s17, 0xe000
	s_nop 0
	global_load_lds_dwordx4 v[166:167], off
	s_waitcnt vmcnt(8)
	s_waitcnt lgkmcnt(0)
	s_barrier
	v_mfma_scale_f32_16x16x128_f8f6f4 v[144:147], v[2:9], v[196:203], v[144:147], v183, v183 op_sel_hi:[0,0,0]
	v_mfma_scale_f32_16x16x128_f8f6f4 v[148:151], v[10:17], v[196:203], v[148:151], v183, v183 op_sel_hi:[0,0,0]
	v_mfma_scale_f32_16x16x128_f8f6f4 v[124:127], v[2:9], v[204:211], v[124:127], v183, v183 op_sel_hi:[0,0,0]
	v_mfma_scale_f32_16x16x128_f8f6f4 v[128:131], v[10:17], v[204:211], v[128:131], v183, v183 op_sel_hi:[0,0,0]
	v_mfma_scale_f32_16x16x128_f8f6f4 v[108:111], v[2:9], v[212:219], v[108:111], v183, v183 op_sel_hi:[0,0,0]
	v_mfma_scale_f32_16x16x128_f8f6f4 v[112:115], v[10:17], v[212:219], v[112:115], v183, v183 op_sel_hi:[0,0,0]
	v_mfma_scale_f32_16x16x128_f8f6f4 v[92:95], v[2:9], v[226:233], v[92:95], v183, v183 op_sel_hi:[0,0,0]
	v_mfma_scale_f32_16x16x128_f8f6f4 v[96:99], v[10:17], v[226:233], v[96:99], v183, v183 op_sel_hi:[0,0,0]
	v_mfma_scale_f32_16x16x128_f8f6f4 v[152:155], v[18:25], v[196:203], v[152:155], v183, v183 op_sel_hi:[0,0,0]
	v_mfma_scale_f32_16x16x128_f8f6f4 v[140:143], v[188:195], v[196:203], v[140:143], v183, v183 op_sel_hi:[0,0,0]
	v_mfma_scale_f32_16x16x128_f8f6f4 v[132:135], v[18:25], v[204:211], v[132:135], v183, v183 op_sel_hi:[0,0,0]
	v_mfma_scale_f32_16x16x128_f8f6f4 v[136:139], v[188:195], v[204:211], v[136:139], v183, v183 op_sel_hi:[0,0,0]
	v_mfma_scale_f32_16x16x128_f8f6f4 v[116:119], v[18:25], v[212:219], v[116:119], v183, v183 op_sel_hi:[0,0,0]
	v_mfma_scale_f32_16x16x128_f8f6f4 v[120:123], v[188:195], v[212:219], v[120:123], v183, v183 op_sel_hi:[0,0,0]
	v_mfma_scale_f32_16x16x128_f8f6f4 v[100:103], v[18:25], v[226:233], v[100:103], v183, v183 op_sel_hi:[0,0,0]
	v_mfma_scale_f32_16x16x128_f8f6f4 v[104:107], v[188:195], v[226:233], v[104:107], v183, v183 op_sel_hi:[0,0,0]
	s_barrier
	s_add_i32 s37, s37, s16
	v_lshl_add_u64 v[166:167], s[28:29], 0, v[26:27]
	s_mov_b32 m0, s37
	ds_read_b128 v[196:199], v187 offset:16384
	ds_read_b128 v[200:203], v187 offset:17408
	ds_read_b128 v[204:207], v187 offset:18432
	ds_read_b128 v[208:211], v187 offset:19456
	ds_read_b128 v[212:215], v187 offset:20480
	ds_read_b128 v[216:219], v187 offset:21504
	ds_read_b128 v[226:229], v187 offset:22528
	ds_read_b128 v[230:233], v187 offset:23552
	global_load_lds_dwordx4 v[166:167], off
	s_add_i32 m0, s37, 0x2000
	s_add_u32 s38, s28, 0x20000
	v_lshl_add_u64 v[176:177], s[28:29], 0, v[160:161]
	s_addc_u32 s39, s29, 0
	s_add_i32 s12, s12, s16
	global_load_lds_dwordx4 v[176:177], off
	v_lshl_add_u64 v[178:179], s[38:39], 0, v[26:27]
	s_mov_b32 m0, s12
	v_lshl_add_u64 v[180:181], s[30:31], 0, v[158:159]
	global_load_lds_dwordx4 v[178:179], off
	v_lshl_add_u64 v[178:179], s[38:39], 0, v[160:161]
	s_add_i32 m0, s12, 0x2000
	s_nop 0
	global_load_lds_dwordx4 v[178:179], off
	v_lshl_add_u64 v[178:179], s[30:31], 0, v[156:157]
	s_mov_b32 m0, s17
	s_nop 0
	global_load_lds_dwordx4 v[178:179], off
	s_mov_b32 m0, s22
	s_nop 0
	global_load_lds_dwordx4 v[180:181], off
	s_waitcnt vmcnt(8)
	s_waitcnt lgkmcnt(0)
	s_barrier
	v_mfma_scale_f32_16x16x128_f8f6f4 v[76:79], v[2:9], v[196:203], v[76:79], v183, v183 op_sel_hi:[0,0,0]
	v_mfma_scale_f32_16x16x128_f8f6f4 v[80:83], v[10:17], v[196:203], v[80:83], v183, v183 op_sel_hi:[0,0,0]
	v_mfma_scale_f32_16x16x128_f8f6f4 v[60:63], v[2:9], v[204:211], v[60:63], v183, v183 op_sel_hi:[0,0,0]
	v_mfma_scale_f32_16x16x128_f8f6f4 v[64:67], v[10:17], v[204:211], v[64:67], v183, v183 op_sel_hi:[0,0,0]
	v_mfma_scale_f32_16x16x128_f8f6f4 v[44:47], v[2:9], v[212:219], v[44:47], v183, v183 op_sel_hi:[0,0,0]
	v_mfma_scale_f32_16x16x128_f8f6f4 v[48:51], v[10:17], v[212:219], v[48:51], v183, v183 op_sel_hi:[0,0,0]
	v_mfma_scale_f32_16x16x128_f8f6f4 v[28:31], v[2:9], v[226:233], v[28:31], v183, v183 op_sel_hi:[0,0,0]
	v_mfma_scale_f32_16x16x128_f8f6f4 v[32:35], v[10:17], v[226:233], v[32:35], v183, v183 op_sel_hi:[0,0,0]
	v_mfma_scale_f32_16x16x128_f8f6f4 v[84:87], v[18:25], v[196:203], v[84:87], v183, v183 op_sel_hi:[0,0,0]
	v_mfma_scale_f32_16x16x128_f8f6f4 v[88:91], v[188:195], v[196:203], v[88:91], v183, v183 op_sel_hi:[0,0,0]
	v_mfma_scale_f32_16x16x128_f8f6f4 v[68:71], v[18:25], v[204:211], v[68:71], v183, v183 op_sel_hi:[0,0,0]
	v_mfma_scale_f32_16x16x128_f8f6f4 v[72:75], v[188:195], v[204:211], v[72:75], v183, v183 op_sel_hi:[0,0,0]
	v_mfma_scale_f32_16x16x128_f8f6f4 v[52:55], v[18:25], v[212:219], v[52:55], v183, v183 op_sel_hi:[0,0,0]
	v_mfma_scale_f32_16x16x128_f8f6f4 v[56:59], v[188:195], v[212:219], v[56:59], v183, v183 op_sel_hi:[0,0,0]
	v_mfma_scale_f32_16x16x128_f8f6f4 v[40:43], v[18:25], v[226:233], v[40:43], v183, v183 op_sel_hi:[0,0,0]
	v_mfma_scale_f32_16x16x128_f8f6f4 v[36:39], v[188:195], v[226:233], v[36:39], v183, v183 op_sel_hi:[0,0,0]
	s_barrier
	s_add_i32 s37, 0, 0x18000
	s_add_i32 s12, 0, 0x1c000
	v_add_u32_e32 v2, s37, v186
	v_add_u32_e32 v22, s12, v186
	ds_read_b128 v[10:13], v2
	ds_read_b128 v[14:17], v2 offset:1024
	ds_read_b128 v[188:191], v2 offset:2048
	ds_read_b128 v[192:195], v2 offset:3072
	ds_read_b128 v[2:5], v22
	ds_read_b128 v[6:9], v22 offset:1024
	ds_read_b128 v[18:21], v22 offset:2048
	ds_read_b128 v[22:25], v22 offset:3072
	s_add_u32 s30, s30, 0x20000
	s_addc_u32 s31, s31, 0
	s_mov_b32 m0, s23
	v_lshl_add_u64 v[220:221], s[30:31], 0, v[156:157]
	ds_read_b128 v[196:199], v187 offset:32768
	ds_read_b128 v[200:203], v187 offset:33792
	ds_read_b128 v[204:207], v187 offset:34816
	ds_read_b128 v[208:211], v187 offset:35840
	ds_read_b128 v[212:215], v187 offset:36864
	ds_read_b128 v[216:219], v187 offset:37888
	ds_read_b128 v[226:229], v187 offset:38912
	ds_read_b128 v[230:233], v187 offset:39936
	global_load_lds_dwordx4 v[220:221], off
	v_lshl_add_u64 v[220:221], s[30:31], 0, v[158:159]
	s_mov_b32 m0, s26
	s_nop 0
	global_load_lds_dwordx4 v[220:221], off
	s_waitcnt vmcnt(8)
	s_waitcnt lgkmcnt(0)
	s_barrier
	v_mfma_scale_f32_16x16x128_f8f6f4 v[144:147], v[10:17], v[196:203], v[144:147], v183, v183 op_sel_hi:[0,0,0]
	v_mfma_scale_f32_16x16x128_f8f6f4 v[148:151], v[188:195], v[196:203], v[148:151], v183, v183 op_sel_hi:[0,0,0]
	v_mfma_scale_f32_16x16x128_f8f6f4 v[124:127], v[10:17], v[204:211], v[124:127], v183, v183 op_sel_hi:[0,0,0]
	v_mfma_scale_f32_16x16x128_f8f6f4 v[128:131], v[188:195], v[204:211], v[128:131], v183, v183 op_sel_hi:[0,0,0]
	v_mfma_scale_f32_16x16x128_f8f6f4 v[108:111], v[10:17], v[212:219], v[108:111], v183, v183 op_sel_hi:[0,0,0]
	v_mfma_scale_f32_16x16x128_f8f6f4 v[112:115], v[188:195], v[212:219], v[112:115], v183, v183 op_sel_hi:[0,0,0]
	v_mfma_scale_f32_16x16x128_f8f6f4 v[92:95], v[10:17], v[226:233], v[92:95], v183, v183 op_sel_hi:[0,0,0]
	v_mfma_scale_f32_16x16x128_f8f6f4 v[96:99], v[188:195], v[226:233], v[96:99], v183, v183 op_sel_hi:[0,0,0]
	v_mfma_scale_f32_16x16x128_f8f6f4 v[152:155], v[2:9], v[196:203], v[152:155], v183, v183 op_sel_hi:[0,0,0]
	v_mfma_scale_f32_16x16x128_f8f6f4 v[140:143], v[18:25], v[196:203], v[140:143], v183, v183 op_sel_hi:[0,0,0]
	v_mfma_scale_f32_16x16x128_f8f6f4 v[132:135], v[2:9], v[204:211], v[132:135], v183, v183 op_sel_hi:[0,0,0]
	v_mfma_scale_f32_16x16x128_f8f6f4 v[136:139], v[18:25], v[204:211], v[136:139], v183, v183 op_sel_hi:[0,0,0]
	v_mfma_scale_f32_16x16x128_f8f6f4 v[116:119], v[2:9], v[212:219], v[116:119], v183, v183 op_sel_hi:[0,0,0]
	v_mfma_scale_f32_16x16x128_f8f6f4 v[120:123], v[18:25], v[212:219], v[120:123], v183, v183 op_sel_hi:[0,0,0]
	v_mfma_scale_f32_16x16x128_f8f6f4 v[100:103], v[2:9], v[226:233], v[100:103], v183, v183 op_sel_hi:[0,0,0]
	v_mfma_scale_f32_16x16x128_f8f6f4 v[104:107], v[18:25], v[226:233], v[104:107], v183, v183 op_sel_hi:[0,0,0]
	s_barrier
	s_add_i32 s30, s37, s16
	v_lshl_add_u64 v[166:167], v[166:167], 0, s[82:83]
	s_mov_b32 m0, s30
	ds_read_b128 v[196:199], v187 offset:49152
	ds_read_b128 v[200:203], v187 offset:50176
	ds_read_b128 v[204:207], v187 offset:51200
	ds_read_b128 v[208:211], v187 offset:52224
	ds_read_b128 v[212:215], v187 offset:53248
	ds_read_b128 v[216:219], v187 offset:54272
	ds_read_b128 v[226:229], v187 offset:55296
	ds_read_b128 v[230:233], v187 offset:56320
	global_load_lds_dwordx4 v[166:167], off
	s_add_i32 m0, s30, 0x2000
	s_add_u32 s28, s28, 0x20080
	v_lshl_add_u64 v[166:167], v[176:177], 0, s[82:83]
	s_addc_u32 s29, s29, 0
	s_add_i32 s12, s12, s16
	global_load_lds_dwordx4 v[166:167], off
	v_lshl_add_u64 v[166:167], s[28:29], 0, v[26:27]
	s_mov_b32 m0, s12
	s_nop 0
	global_load_lds_dwordx4 v[166:167], off
	v_lshl_add_u64 v[166:167], s[28:29], 0, v[160:161]
	s_add_i32 m0, s12, 0x2000
	s_nop 0
	global_load_lds_dwordx4 v[166:167], off
	v_lshl_add_u64 v[166:167], v[178:179], 0, s[82:83]
	s_mov_b32 m0, s34
	s_nop 0
	global_load_lds_dwordx4 v[166:167], off
	v_lshl_add_u64 v[166:167], v[180:181], 0, s[82:83]
	s_mov_b32 m0, s35
	s_nop 0
	global_load_lds_dwordx4 v[166:167], off
	s_waitcnt vmcnt(8)
	s_waitcnt lgkmcnt(0)
	s_barrier
	v_mfma_scale_f32_16x16x128_f8f6f4 v[76:79], v[10:17], v[196:203], v[76:79], v183, v183 op_sel_hi:[0,0,0]
	v_mfma_scale_f32_16x16x128_f8f6f4 v[80:83], v[188:195], v[196:203], v[80:83], v183, v183 op_sel_hi:[0,0,0]
	v_mfma_scale_f32_16x16x128_f8f6f4 v[60:63], v[10:17], v[204:211], v[60:63], v183, v183 op_sel_hi:[0,0,0]
	v_mfma_scale_f32_16x16x128_f8f6f4 v[64:67], v[188:195], v[204:211], v[64:67], v183, v183 op_sel_hi:[0,0,0]
	v_mfma_scale_f32_16x16x128_f8f6f4 v[44:47], v[10:17], v[212:219], v[44:47], v183, v183 op_sel_hi:[0,0,0]
	v_mfma_scale_f32_16x16x128_f8f6f4 v[48:51], v[188:195], v[212:219], v[48:51], v183, v183 op_sel_hi:[0,0,0]
	v_mfma_scale_f32_16x16x128_f8f6f4 v[28:31], v[10:17], v[226:233], v[28:31], v183, v183 op_sel_hi:[0,0,0]
	v_mfma_scale_f32_16x16x128_f8f6f4 v[32:35], v[188:195], v[226:233], v[32:35], v183, v183 op_sel_hi:[0,0,0]
	v_mfma_scale_f32_16x16x128_f8f6f4 v[84:87], v[2:9], v[196:203], v[84:87], v183, v183 op_sel_hi:[0,0,0]
	v_mfma_scale_f32_16x16x128_f8f6f4 v[88:91], v[18:25], v[196:203], v[88:91], v183, v183 op_sel_hi:[0,0,0]
	v_mfma_scale_f32_16x16x128_f8f6f4 v[68:71], v[2:9], v[204:211], v[68:71], v183, v183 op_sel_hi:[0,0,0]
	v_mfma_scale_f32_16x16x128_f8f6f4 v[72:75], v[18:25], v[204:211], v[72:75], v183, v183 op_sel_hi:[0,0,0]
	v_mfma_scale_f32_16x16x128_f8f6f4 v[52:55], v[2:9], v[212:219], v[52:55], v183, v183 op_sel_hi:[0,0,0]
	v_mfma_scale_f32_16x16x128_f8f6f4 v[56:59], v[18:25], v[212:219], v[56:59], v183, v183 op_sel_hi:[0,0,0]
	v_mfma_scale_f32_16x16x128_f8f6f4 v[40:43], v[2:9], v[226:233], v[40:43], v183, v183 op_sel_hi:[0,0,0]
	v_mfma_scale_f32_16x16x128_f8f6f4 v[36:39], v[18:25], v[226:233], v[36:39], v183, v183 op_sel_hi:[0,0,0]
	s_barrier
	s_add_i32 s36, s36, 2
	s_add_u32 s20, s20, 0x100
	s_addc_u32 s21, s21, 0
	s_cmp_gt_u32 s36, 5
	s_cbranch_scc0 .LBB0_492
	s_cmpk_lt_u32 s8, 0x100
	s_cbranch_scc0 .LBB0_495
	s_barrier

.LBB0_548:
	s_add_u32 s12, s54, 0xffea0080
	s_addc_u32 s58, s55, -1
	s_add_i32 s72, 0, 0x10000
	s_cmp_eq_u32 s80, 4
	s_cselect_b32 s61, s41, s58
	s_cselect_b32 s60, s40, s12
	v_add_u32_e32 v26, s72, v227
	s_cselect_b32 s59, s53, s57
	s_cselect_b32 s58, s52, s1
	s_add_i32 s12, 0, 0x14000
	ds_read_b128 v[146:149], v26
	ds_read_b128 v[150:153], v26 offset:1024
	ds_read_b128 v[154:157], v26 offset:2048
	ds_read_b128 v[158:161], v26 offset:3072
	v_add_u32_e32 v26, s12, v227
	ds_read_b128 v[162:165], v26
	ds_read_b128 v[176:179], v26 offset:1024
	ds_read_b128 v[180:183], v26 offset:2048
	ds_read_b128 v[184:187], v26 offset:3072
	v_lshl_add_u64 v[166:167], s[54:55], 0, v[142:143]
	s_add_i32 m0, s16, 0xc000
	ds_read_b128 v[188:191], v229
	ds_read_b128 v[192:195], v229 offset:1024
	ds_read_b128 v[196:199], v229 offset:2048
	ds_read_b128 v[200:203], v229 offset:3072
	ds_read_b128 v[204:207], v229 offset:4096
	ds_read_b128 v[208:211], v229 offset:5120
	ds_read_b128 v[212:215], v229 offset:6144
	ds_read_b128 v[216:219], v229 offset:7168
	global_load_lds_dwordx4 v[166:167], off
	v_lshl_add_u64 v[166:167], s[54:55], 0, v[144:145]
	s_add_i32 m0, s16, 0xe000
	s_nop 0
	global_load_lds_dwordx4 v[166:167], off
	s_waitcnt vmcnt(8)
	s_waitcnt lgkmcnt(0)
	s_barrier
	v_mfma_f32_16x16x32_bf16 v[2:5], v[146:149], v[188:191], v[2:5]
	v_mfma_f32_16x16x32_bf16 v[6:9], v[154:157], v[188:191], v[6:9]
	v_mfma_f32_16x16x32_bf16 v[10:13], v[146:149], v[196:199], v[10:13]
	v_mfma_f32_16x16x32_bf16 v[14:17], v[154:157], v[196:199], v[14:17]
	v_mfma_f32_16x16x32_bf16 v[18:21], v[146:149], v[204:207], v[18:21]
	v_mfma_f32_16x16x32_bf16 v[22:25], v[154:157], v[204:207], v[22:25]
	v_mfma_f32_16x16x32_bf16 v[28:31], v[146:149], v[212:215], v[28:31]
	v_mfma_f32_16x16x32_bf16 v[32:35], v[154:157], v[212:215], v[32:35]
	v_mfma_f32_16x16x32_bf16 v[2:5], v[150:153], v[192:195], v[2:5]
	v_mfma_f32_16x16x32_bf16 v[6:9], v[158:161], v[192:195], v[6:9]
	v_mfma_f32_16x16x32_bf16 v[10:13], v[150:153], v[200:203], v[10:13]
	v_mfma_f32_16x16x32_bf16 v[14:17], v[158:161], v[200:203], v[14:17]
	v_mfma_f32_16x16x32_bf16 v[18:21], v[150:153], v[208:211], v[18:21]
	v_mfma_f32_16x16x32_bf16 v[22:25], v[158:161], v[208:211], v[22:25]
	v_mfma_f32_16x16x32_bf16 v[28:31], v[150:153], v[216:219], v[28:31]
	v_mfma_f32_16x16x32_bf16 v[32:35], v[158:161], v[216:219], v[32:35]
	v_mfma_f32_16x16x32_bf16 v[36:39], v[162:165], v[188:191], v[36:39]
	v_mfma_f32_16x16x32_bf16 v[40:43], v[180:183], v[188:191], v[40:43]
	v_mfma_f32_16x16x32_bf16 v[44:47], v[162:165], v[196:199], v[44:47]
	v_mfma_f32_16x16x32_bf16 v[48:51], v[180:183], v[196:199], v[48:51]
	v_mfma_f32_16x16x32_bf16 v[52:55], v[162:165], v[204:207], v[52:55]
	v_mfma_f32_16x16x32_bf16 v[56:59], v[180:183], v[204:207], v[56:59]
	v_mfma_f32_16x16x32_bf16 v[60:63], v[162:165], v[212:215], v[60:63]
	v_mfma_f32_16x16x32_bf16 v[64:67], v[180:183], v[212:215], v[64:67]
	v_mfma_f32_16x16x32_bf16 v[36:39], v[176:179], v[192:195], v[36:39]
	v_mfma_f32_16x16x32_bf16 v[40:43], v[184:187], v[192:195], v[40:43]
	v_mfma_f32_16x16x32_bf16 v[44:47], v[176:179], v[200:203], v[44:47]
	v_mfma_f32_16x16x32_bf16 v[48:51], v[184:187], v[200:203], v[48:51]
	v_mfma_f32_16x16x32_bf16 v[52:55], v[176:179], v[208:211], v[52:55]
	v_mfma_f32_16x16x32_bf16 v[56:59], v[184:187], v[208:211], v[56:59]
	v_mfma_f32_16x16x32_bf16 v[60:63], v[176:179], v[216:219], v[60:63]
	v_mfma_f32_16x16x32_bf16 v[64:67], v[184:187], v[216:219], v[64:67]
	s_barrier
	s_add_i32 s72, s72, s15
	v_lshl_add_u64 v[166:167], s[58:59], 0, v[134:135]
	s_mov_b32 m0, s72
	ds_read_b128 v[188:191], v229 offset:16384
	ds_read_b128 v[192:195], v229 offset:17408
	ds_read_b128 v[196:199], v229 offset:18432
	ds_read_b128 v[200:203], v229 offset:19456
	ds_read_b128 v[204:207], v229 offset:20480
	ds_read_b128 v[208:211], v229 offset:21504
	ds_read_b128 v[212:215], v229 offset:22528
	ds_read_b128 v[216:219], v229 offset:23552
	global_load_lds_dwordx4 v[166:167], off
	s_add_i32 m0, s72, 0x2000
	s_add_u32 s72, s58, 0x60000
	v_lshl_add_u64 v[220:221], s[58:59], 0, v[138:139]
	s_addc_u32 s73, s59, 0
	s_add_i32 s12, s12, s15
	global_load_lds_dwordx4 v[220:221], off
	v_lshl_add_u64 v[230:231], s[72:73], 0, v[134:135]
	s_mov_b32 m0, s12
	v_lshl_add_u64 v[232:233], s[60:61], 0, v[136:137]
	global_load_lds_dwordx4 v[230:231], off
	v_lshl_add_u64 v[230:231], s[72:73], 0, v[138:139]
	s_add_i32 m0, s12, 0x2000
	s_nop 0
	global_load_lds_dwordx4 v[230:231], off
	v_lshl_add_u64 v[230:231], s[60:61], 0, v[132:133]
	s_mov_b32 m0, s16
	s_nop 0
	global_load_lds_dwordx4 v[230:231], off
	s_mov_b32 m0, s17
	s_nop 0
	global_load_lds_dwordx4 v[232:233], off
	s_waitcnt vmcnt(8)
	s_waitcnt lgkmcnt(0)
	s_barrier
	v_mfma_f32_16x16x32_bf16 v[68:71], v[146:149], v[188:191], v[68:71]
	v_mfma_f32_16x16x32_bf16 v[72:75], v[154:157], v[188:191], v[72:75]
	v_mfma_f32_16x16x32_bf16 v[76:79], v[146:149], v[196:199], v[76:79]
	v_mfma_f32_16x16x32_bf16 v[80:83], v[154:157], v[196:199], v[80:83]
	v_mfma_f32_16x16x32_bf16 v[84:87], v[146:149], v[204:207], v[84:87]
	v_mfma_f32_16x16x32_bf16 v[88:91], v[154:157], v[204:207], v[88:91]
	v_mfma_f32_16x16x32_bf16 v[92:95], v[146:149], v[212:215], v[92:95]
	v_mfma_f32_16x16x32_bf16 v[96:99], v[154:157], v[212:215], v[96:99]
	v_mfma_f32_16x16x32_bf16 v[68:71], v[150:153], v[192:195], v[68:71]
	v_mfma_f32_16x16x32_bf16 v[72:75], v[158:161], v[192:195], v[72:75]
	v_mfma_f32_16x16x32_bf16 v[76:79], v[150:153], v[200:203], v[76:79]
	v_mfma_f32_16x16x32_bf16 v[80:83], v[158:161], v[200:203], v[80:83]
	v_mfma_f32_16x16x32_bf16 v[84:87], v[150:153], v[208:211], v[84:87]
	v_mfma_f32_16x16x32_bf16 v[88:91], v[158:161], v[208:211], v[88:91]
	v_mfma_f32_16x16x32_bf16 v[92:95], v[150:153], v[216:219], v[92:95]
	v_mfma_f32_16x16x32_bf16 v[96:99], v[158:161], v[216:219], v[96:99]
	v_mfma_f32_16x16x32_bf16 v[100:103], v[162:165], v[188:191], v[100:103]
	v_mfma_f32_16x16x32_bf16 v[104:107], v[180:183], v[188:191], v[104:107]
	v_mfma_f32_16x16x32_bf16 v[108:111], v[162:165], v[196:199], v[108:111]
	v_mfma_f32_16x16x32_bf16 v[112:115], v[180:183], v[196:199], v[112:115]
	v_mfma_f32_16x16x32_bf16 v[116:119], v[162:165], v[204:207], v[116:119]
	v_mfma_f32_16x16x32_bf16 v[120:123], v[180:183], v[204:207], v[120:123]
	v_mfma_f32_16x16x32_bf16 v[124:127], v[162:165], v[212:215], v[124:127]
	v_mfma_f32_16x16x32_bf16 v[128:131], v[180:183], v[212:215], v[128:131]
	v_mfma_f32_16x16x32_bf16 v[100:103], v[176:179], v[192:195], v[100:103]
	v_mfma_f32_16x16x32_bf16 v[104:107], v[184:187], v[192:195], v[104:107]
	v_mfma_f32_16x16x32_bf16 v[108:111], v[176:179], v[200:203], v[108:111]
	v_mfma_f32_16x16x32_bf16 v[112:115], v[184:187], v[200:203], v[112:115]
	v_mfma_f32_16x16x32_bf16 v[116:119], v[176:179], v[208:211], v[116:119]
	v_mfma_f32_16x16x32_bf16 v[120:123], v[184:187], v[208:211], v[120:123]
	v_mfma_f32_16x16x32_bf16 v[124:127], v[176:179], v[216:219], v[124:127]
	v_mfma_f32_16x16x32_bf16 v[128:131], v[184:187], v[216:219], v[128:131]
	s_barrier
	s_add_i32 s12, 0, 0x18000
	v_add_u32_e32 v26, s12, v227
	s_add_i32 s72, 0, 0x1c000
	ds_read_b128 v[146:149], v26
	ds_read_b128 v[150:153], v26 offset:1024
	ds_read_b128 v[154:157], v26 offset:2048
	ds_read_b128 v[158:161], v26 offset:3072
	v_add_u32_e32 v26, s72, v227
	ds_read_b128 v[162:165], v26
	ds_read_b128 v[176:179], v26 offset:1024
	ds_read_b128 v[180:183], v26 offset:2048
	ds_read_b128 v[184:187], v26 offset:3072
	s_add_u32 s60, s60, 0x160000
	s_addc_u32 s61, s61, 0
	s_mov_b32 m0, s22
	v_lshl_add_u64 v[234:235], s[60:61], 0, v[132:133]
	ds_read_b128 v[188:191], v229 offset:32768
	ds_read_b128 v[192:195], v229 offset:33792
	ds_read_b128 v[196:199], v229 offset:34816
	ds_read_b128 v[200:203], v229 offset:35840
	ds_read_b128 v[204:207], v229 offset:36864
	ds_read_b128 v[208:211], v229 offset:37888
	ds_read_b128 v[212:215], v229 offset:38912
	ds_read_b128 v[216:219], v229 offset:39936
	global_load_lds_dwordx4 v[234:235], off
	v_lshl_add_u64 v[234:235], s[60:61], 0, v[136:137]
	s_mov_b32 m0, s23
	s_nop 0
	global_load_lds_dwordx4 v[234:235], off
	s_waitcnt vmcnt(8)
	s_waitcnt lgkmcnt(0)
	s_barrier
	v_mfma_f32_16x16x32_bf16 v[2:5], v[146:149], v[188:191], v[2:5]
	v_mfma_f32_16x16x32_bf16 v[6:9], v[154:157], v[188:191], v[6:9]
	v_mfma_f32_16x16x32_bf16 v[10:13], v[146:149], v[196:199], v[10:13]
	v_mfma_f32_16x16x32_bf16 v[14:17], v[154:157], v[196:199], v[14:17]
	v_mfma_f32_16x16x32_bf16 v[18:21], v[146:149], v[204:207], v[18:21]
	v_mfma_f32_16x16x32_bf16 v[22:25], v[154:157], v[204:207], v[22:25]
	v_mfma_f32_16x16x32_bf16 v[28:31], v[146:149], v[212:215], v[28:31]
	v_mfma_f32_16x16x32_bf16 v[32:35], v[154:157], v[212:215], v[32:35]
	v_mfma_f32_16x16x32_bf16 v[2:5], v[150:153], v[192:195], v[2:5]
	v_mfma_f32_16x16x32_bf16 v[6:9], v[158:161], v[192:195], v[6:9]
	v_mfma_f32_16x16x32_bf16 v[10:13], v[150:153], v[200:203], v[10:13]
	v_mfma_f32_16x16x32_bf16 v[14:17], v[158:161], v[200:203], v[14:17]
	v_mfma_f32_16x16x32_bf16 v[18:21], v[150:153], v[208:211], v[18:21]
	v_mfma_f32_16x16x32_bf16 v[22:25], v[158:161], v[208:211], v[22:25]
	v_mfma_f32_16x16x32_bf16 v[28:31], v[150:153], v[216:219], v[28:31]
	v_mfma_f32_16x16x32_bf16 v[32:35], v[158:161], v[216:219], v[32:35]
	v_mfma_f32_16x16x32_bf16 v[36:39], v[162:165], v[188:191], v[36:39]
	v_mfma_f32_16x16x32_bf16 v[40:43], v[180:183], v[188:191], v[40:43]
	v_mfma_f32_16x16x32_bf16 v[44:47], v[162:165], v[196:199], v[44:47]
	v_mfma_f32_16x16x32_bf16 v[48:51], v[180:183], v[196:199], v[48:51]
	v_mfma_f32_16x16x32_bf16 v[52:55], v[162:165], v[204:207], v[52:55]
	v_mfma_f32_16x16x32_bf16 v[56:59], v[180:183], v[204:207], v[56:59]
	v_mfma_f32_16x16x32_bf16 v[60:63], v[162:165], v[212:215], v[60:63]
	v_mfma_f32_16x16x32_bf16 v[64:67], v[180:183], v[212:215], v[64:67]
	v_mfma_f32_16x16x32_bf16 v[36:39], v[176:179], v[192:195], v[36:39]
	v_mfma_f32_16x16x32_bf16 v[40:43], v[184:187], v[192:195], v[40:43]
	v_mfma_f32_16x16x32_bf16 v[44:47], v[176:179], v[200:203], v[44:47]
	v_mfma_f32_16x16x32_bf16 v[48:51], v[184:187], v[200:203], v[48:51]
	v_mfma_f32_16x16x32_bf16 v[52:55], v[176:179], v[208:211], v[52:55]
	v_mfma_f32_16x16x32_bf16 v[56:59], v[184:187], v[208:211], v[56:59]
	v_mfma_f32_16x16x32_bf16 v[60:63], v[176:179], v[216:219], v[60:63]
	v_mfma_f32_16x16x32_bf16 v[64:67], v[184:187], v[216:219], v[64:67]
	s_barrier
	s_add_i32 s12, s12, s15
	v_lshl_add_u64 v[166:167], v[166:167], 0, s[82:83]
	s_mov_b32 m0, s12
	ds_read_b128 v[188:191], v229 offset:49152
	ds_read_b128 v[192:195], v229 offset:50176
	ds_read_b128 v[196:199], v229 offset:51200
	ds_read_b128 v[200:203], v229 offset:52224
	ds_read_b128 v[204:207], v229 offset:53248
	ds_read_b128 v[208:211], v229 offset:54272
	ds_read_b128 v[212:215], v229 offset:55296
	ds_read_b128 v[216:219], v229 offset:56320
	global_load_lds_dwordx4 v[166:167], off
	s_add_i32 m0, s12, 0x2000
	s_add_u32 s58, s58, 0x60080
	v_lshl_add_u64 v[166:167], v[220:221], 0, s[82:83]
	s_addc_u32 s59, s59, 0
	s_add_i32 s12, s72, s15
	global_load_lds_dwordx4 v[166:167], off
	v_lshl_add_u64 v[166:167], s[58:59], 0, v[134:135]
	s_mov_b32 m0, s12
	s_nop 0
	global_load_lds_dwordx4 v[166:167], off
	v_lshl_add_u64 v[166:167], s[58:59], 0, v[138:139]
	s_add_i32 m0, s12, 0x2000
	s_nop 0
	global_load_lds_dwordx4 v[166:167], off
	v_lshl_add_u64 v[166:167], v[230:231], 0, s[82:83]
	s_mov_b32 m0, s26
	s_nop 0
	global_load_lds_dwordx4 v[166:167], off
	v_lshl_add_u64 v[166:167], v[232:233], 0, s[82:83]
	s_mov_b32 m0, s27
	s_nop 0
	global_load_lds_dwordx4 v[166:167], off
	s_waitcnt vmcnt(8)
	s_waitcnt lgkmcnt(0)
	s_barrier
	v_mfma_f32_16x16x32_bf16 v[68:71], v[146:149], v[188:191], v[68:71]
	v_mfma_f32_16x16x32_bf16 v[72:75], v[154:157], v[188:191], v[72:75]
	v_mfma_f32_16x16x32_bf16 v[76:79], v[146:149], v[196:199], v[76:79]
	v_mfma_f32_16x16x32_bf16 v[80:83], v[154:157], v[196:199], v[80:83]
	v_mfma_f32_16x16x32_bf16 v[84:87], v[146:149], v[204:207], v[84:87]
	v_mfma_f32_16x16x32_bf16 v[88:91], v[154:157], v[204:207], v[88:91]
	v_mfma_f32_16x16x32_bf16 v[92:95], v[146:149], v[212:215], v[92:95]
	v_mfma_f32_16x16x32_bf16 v[96:99], v[154:157], v[212:215], v[96:99]
	v_mfma_f32_16x16x32_bf16 v[68:71], v[150:153], v[192:195], v[68:71]
	v_mfma_f32_16x16x32_bf16 v[72:75], v[158:161], v[192:195], v[72:75]
	v_mfma_f32_16x16x32_bf16 v[76:79], v[150:153], v[200:203], v[76:79]
	v_mfma_f32_16x16x32_bf16 v[80:83], v[158:161], v[200:203], v[80:83]
	v_mfma_f32_16x16x32_bf16 v[84:87], v[150:153], v[208:211], v[84:87]
	v_mfma_f32_16x16x32_bf16 v[88:91], v[158:161], v[208:211], v[88:91]
	v_mfma_f32_16x16x32_bf16 v[92:95], v[150:153], v[216:219], v[92:95]
	v_mfma_f32_16x16x32_bf16 v[96:99], v[158:161], v[216:219], v[96:99]
	v_mfma_f32_16x16x32_bf16 v[100:103], v[162:165], v[188:191], v[100:103]
	v_mfma_f32_16x16x32_bf16 v[104:107], v[180:183], v[188:191], v[104:107]
	v_mfma_f32_16x16x32_bf16 v[108:111], v[162:165], v[196:199], v[108:111]
	v_mfma_f32_16x16x32_bf16 v[112:115], v[180:183], v[196:199], v[112:115]
	v_mfma_f32_16x16x32_bf16 v[116:119], v[162:165], v[204:207], v[116:119]
	v_mfma_f32_16x16x32_bf16 v[120:123], v[180:183], v[204:207], v[120:123]
	v_mfma_f32_16x16x32_bf16 v[124:127], v[162:165], v[212:215], v[124:127]
	v_mfma_f32_16x16x32_bf16 v[128:131], v[180:183], v[212:215], v[128:131]
	v_mfma_f32_16x16x32_bf16 v[100:103], v[176:179], v[192:195], v[100:103]
	v_mfma_f32_16x16x32_bf16 v[104:107], v[184:187], v[192:195], v[104:107]
	v_mfma_f32_16x16x32_bf16 v[108:111], v[176:179], v[200:203], v[108:111]
	v_mfma_f32_16x16x32_bf16 v[112:115], v[184:187], v[200:203], v[112:115]
	v_mfma_f32_16x16x32_bf16 v[116:119], v[176:179], v[208:211], v[116:119]
	v_mfma_f32_16x16x32_bf16 v[120:123], v[184:187], v[208:211], v[120:123]
	v_mfma_f32_16x16x32_bf16 v[124:127], v[176:179], v[216:219], v[124:127]
	v_mfma_f32_16x16x32_bf16 v[128:131], v[184:187], v[216:219], v[128:131]
	s_barrier
	s_add_i32 s80, s80, 2
	s_add_u32 s54, s54, 0x100
	s_addc_u32 s55, s55, 0
	s_add_u32 s1, s1, 0x100
	s_addc_u32 s57, s57, 0
	s_cmp_gt_u32 s80, 5
	s_cbranch_scc0 .LBB0_548
	s_and_b64 vcc, exec, s[30:31]
	s_cbranch_vccz .LBB0_551
	s_barrier

.LBB0_678:
	s_add_u32 s12, s86, 0xffea0080
	s_addc_u32 s72, s87, -1
	s_add_i32 s73, 0, 0x10000
	s_cmp_eq_u32 s61, 12
	s_cselect_b32 s77, s89, s72
	s_cselect_b32 s76, s88, s12
	v_add_u32_e32 v26, s73, v202
	s_cselect_b32 s75, s91, s59
	s_cselect_b32 s74, s90, s35
	s_add_i32 s12, 0, 0x14000
	ds_read_b128 v[132:135], v26
	ds_read_b128 v[136:139], v26 offset:1024
	ds_read_b128 v[140:143], v26 offset:2048
	ds_read_b128 v[144:147], v26 offset:3072
	v_add_u32_e32 v26, s12, v202
	ds_read_b128 v[148:151], v26
	ds_read_b128 v[152:155], v26 offset:1024
	ds_read_b128 v[156:159], v26 offset:2048
	ds_read_b128 v[160:163], v26 offset:3072
	v_lshl_add_u64 v[220:221], s[86:87], 0, v[188:189]
	s_add_i32 m0, s11, 0xc000
	ds_read_b128 v[164:167], v185
	ds_read_b128 v[192:195], v185 offset:1024
	ds_read_b128 v[196:199], v185 offset:2048
	ds_read_b128 v[204:207], v185 offset:3072
	ds_read_b128 v[208:211], v185 offset:4096
	ds_read_b128 v[212:215], v185 offset:5120
	ds_read_b128 v[216:219], v185 offset:6144
	ds_read_b128 v[226:229], v185 offset:7168
	global_load_lds_dwordx4 v[220:221], off
	v_lshl_add_u64 v[220:221], s[86:87], 0, v[190:191]
	s_add_i32 m0, s11, 0xe000
	s_nop 0
	global_load_lds_dwordx4 v[220:221], off
	s_waitcnt vmcnt(8)
	s_waitcnt lgkmcnt(0)
	s_barrier
	v_mfma_f32_16x16x32_bf16 v[2:5], v[132:135], v[164:167], v[2:5]
	v_mfma_f32_16x16x32_bf16 v[6:9], v[140:143], v[164:167], v[6:9]
	v_mfma_f32_16x16x32_bf16 v[10:13], v[132:135], v[196:199], v[10:13]
	v_mfma_f32_16x16x32_bf16 v[14:17], v[140:143], v[196:199], v[14:17]
	v_mfma_f32_16x16x32_bf16 v[18:21], v[132:135], v[208:211], v[18:21]
	v_mfma_f32_16x16x32_bf16 v[22:25], v[140:143], v[208:211], v[22:25]
	v_mfma_f32_16x16x32_bf16 v[28:31], v[132:135], v[216:219], v[28:31]
	v_mfma_f32_16x16x32_bf16 v[32:35], v[140:143], v[216:219], v[32:35]
	v_mfma_f32_16x16x32_bf16 v[2:5], v[136:139], v[192:195], v[2:5]
	v_mfma_f32_16x16x32_bf16 v[6:9], v[144:147], v[192:195], v[6:9]
	v_mfma_f32_16x16x32_bf16 v[10:13], v[136:139], v[204:207], v[10:13]
	v_mfma_f32_16x16x32_bf16 v[14:17], v[144:147], v[204:207], v[14:17]
	v_mfma_f32_16x16x32_bf16 v[18:21], v[136:139], v[212:215], v[18:21]
	v_mfma_f32_16x16x32_bf16 v[22:25], v[144:147], v[212:215], v[22:25]
	v_mfma_f32_16x16x32_bf16 v[28:31], v[136:139], v[226:229], v[28:31]
	v_mfma_f32_16x16x32_bf16 v[32:35], v[144:147], v[226:229], v[32:35]
	v_mfma_f32_16x16x32_bf16 v[36:39], v[148:151], v[164:167], v[36:39]
	v_mfma_f32_16x16x32_bf16 v[40:43], v[156:159], v[164:167], v[40:43]
	v_mfma_f32_16x16x32_bf16 v[44:47], v[148:151], v[196:199], v[44:47]
	v_mfma_f32_16x16x32_bf16 v[48:51], v[156:159], v[196:199], v[48:51]
	v_mfma_f32_16x16x32_bf16 v[52:55], v[148:151], v[208:211], v[52:55]
	v_mfma_f32_16x16x32_bf16 v[56:59], v[156:159], v[208:211], v[56:59]
	v_mfma_f32_16x16x32_bf16 v[60:63], v[148:151], v[216:219], v[60:63]
	v_mfma_f32_16x16x32_bf16 v[64:67], v[156:159], v[216:219], v[64:67]
	v_mfma_f32_16x16x32_bf16 v[36:39], v[152:155], v[192:195], v[36:39]
	v_mfma_f32_16x16x32_bf16 v[40:43], v[160:163], v[192:195], v[40:43]
	v_mfma_f32_16x16x32_bf16 v[44:47], v[152:155], v[204:207], v[44:47]
	v_mfma_f32_16x16x32_bf16 v[48:51], v[160:163], v[204:207], v[48:51]
	v_mfma_f32_16x16x32_bf16 v[52:55], v[152:155], v[212:215], v[52:55]
	v_mfma_f32_16x16x32_bf16 v[56:59], v[160:163], v[212:215], v[56:59]
	v_mfma_f32_16x16x32_bf16 v[60:63], v[152:155], v[226:229], v[60:63]
	v_mfma_f32_16x16x32_bf16 v[64:67], v[160:163], v[226:229], v[64:67]
	s_barrier
	s_add_i32 s72, s73, s8
	v_lshl_add_u64 v[220:221], s[74:75], 0, v[178:179]
	s_mov_b32 m0, s72
	ds_read_b128 v[164:167], v185 offset:16384
	ds_read_b128 v[192:195], v185 offset:17408
	ds_read_b128 v[196:199], v185 offset:18432
	ds_read_b128 v[204:207], v185 offset:19456
	ds_read_b128 v[208:211], v185 offset:20480
	ds_read_b128 v[212:215], v185 offset:21504
	ds_read_b128 v[216:219], v185 offset:22528
	ds_read_b128 v[226:229], v185 offset:23552
	global_load_lds_dwordx4 v[220:221], off
	s_add_i32 m0, s72, 0x2000
	s_add_u32 s72, s74, 0x40000
	v_lshl_add_u64 v[230:231], s[74:75], 0, v[182:183]
	s_addc_u32 s73, s75, 0
	s_add_i32 s12, s12, s8
	global_load_lds_dwordx4 v[230:231], off
	v_lshl_add_u64 v[232:233], s[72:73], 0, v[178:179]
	s_mov_b32 m0, s12
	v_lshl_add_u64 v[234:235], s[76:77], 0, v[180:181]
	global_load_lds_dwordx4 v[232:233], off
	v_lshl_add_u64 v[232:233], s[72:73], 0, v[182:183]
	s_add_i32 m0, s12, 0x2000
	s_nop 0
	global_load_lds_dwordx4 v[232:233], off
	v_lshl_add_u64 v[232:233], s[76:77], 0, v[176:177]
	s_mov_b32 m0, s11
	s_nop 0
	global_load_lds_dwordx4 v[232:233], off
	s_mov_b32 m0, s16
	s_nop 0
	global_load_lds_dwordx4 v[234:235], off
	s_waitcnt vmcnt(8)
	s_waitcnt lgkmcnt(0)
	s_barrier
	v_mfma_f32_16x16x32_bf16 v[68:71], v[132:135], v[164:167], v[68:71]
	v_mfma_f32_16x16x32_bf16 v[72:75], v[140:143], v[164:167], v[72:75]
	v_mfma_f32_16x16x32_bf16 v[76:79], v[132:135], v[196:199], v[76:79]
	v_mfma_f32_16x16x32_bf16 v[80:83], v[140:143], v[196:199], v[80:83]
	v_mfma_f32_16x16x32_bf16 v[84:87], v[132:135], v[208:211], v[84:87]
	v_mfma_f32_16x16x32_bf16 v[88:91], v[140:143], v[208:211], v[88:91]
	v_mfma_f32_16x16x32_bf16 v[92:95], v[132:135], v[216:219], v[92:95]
	v_mfma_f32_16x16x32_bf16 v[96:99], v[140:143], v[216:219], v[96:99]
	v_mfma_f32_16x16x32_bf16 v[68:71], v[136:139], v[192:195], v[68:71]
	v_mfma_f32_16x16x32_bf16 v[72:75], v[144:147], v[192:195], v[72:75]
	v_mfma_f32_16x16x32_bf16 v[76:79], v[136:139], v[204:207], v[76:79]
	v_mfma_f32_16x16x32_bf16 v[80:83], v[144:147], v[204:207], v[80:83]
	v_mfma_f32_16x16x32_bf16 v[84:87], v[136:139], v[212:215], v[84:87]
	v_mfma_f32_16x16x32_bf16 v[88:91], v[144:147], v[212:215], v[88:91]
	v_mfma_f32_16x16x32_bf16 v[92:95], v[136:139], v[226:229], v[92:95]
	v_mfma_f32_16x16x32_bf16 v[96:99], v[144:147], v[226:229], v[96:99]
	v_mfma_f32_16x16x32_bf16 v[100:103], v[148:151], v[164:167], v[100:103]
	v_mfma_f32_16x16x32_bf16 v[104:107], v[156:159], v[164:167], v[104:107]
	v_mfma_f32_16x16x32_bf16 v[108:111], v[148:151], v[196:199], v[108:111]
	v_mfma_f32_16x16x32_bf16 v[112:115], v[156:159], v[196:199], v[112:115]
	v_mfma_f32_16x16x32_bf16 v[116:119], v[148:151], v[208:211], v[116:119]
	v_mfma_f32_16x16x32_bf16 v[120:123], v[156:159], v[208:211], v[120:123]
	v_mfma_f32_16x16x32_bf16 v[124:127], v[148:151], v[216:219], v[124:127]
	v_mfma_f32_16x16x32_bf16 v[128:131], v[156:159], v[216:219], v[128:131]
	v_mfma_f32_16x16x32_bf16 v[100:103], v[152:155], v[192:195], v[100:103]
	v_mfma_f32_16x16x32_bf16 v[104:107], v[160:163], v[192:195], v[104:107]
	v_mfma_f32_16x16x32_bf16 v[108:111], v[152:155], v[204:207], v[108:111]
	v_mfma_f32_16x16x32_bf16 v[112:115], v[160:163], v[204:207], v[112:115]
	v_mfma_f32_16x16x32_bf16 v[116:119], v[152:155], v[212:215], v[116:119]
	v_mfma_f32_16x16x32_bf16 v[120:123], v[160:163], v[212:215], v[120:123]
	v_mfma_f32_16x16x32_bf16 v[124:127], v[152:155], v[226:229], v[124:127]
	v_mfma_f32_16x16x32_bf16 v[128:131], v[160:163], v[226:229], v[128:131]
	s_barrier
	s_add_i32 s12, 0, 0x18000
	v_add_u32_e32 v26, s12, v202
	s_add_i32 s78, 0, 0x1c000
	ds_read_b128 v[132:135], v26
	ds_read_b128 v[136:139], v26 offset:1024
	ds_read_b128 v[140:143], v26 offset:2048
	ds_read_b128 v[144:147], v26 offset:3072
	v_add_u32_e32 v26, s78, v202
	ds_read_b128 v[148:151], v26
	ds_read_b128 v[152:155], v26 offset:1024
	ds_read_b128 v[156:159], v26 offset:2048
	ds_read_b128 v[160:163], v26 offset:3072
	s_add_u32 s72, s76, 0x160000
	s_addc_u32 s73, s77, 0
	s_mov_b32 m0, s17
	v_lshl_add_u64 v[236:237], s[72:73], 0, v[176:177]
	ds_read_b128 v[164:167], v185 offset:32768
	ds_read_b128 v[192:195], v185 offset:33792
	ds_read_b128 v[196:199], v185 offset:34816
	ds_read_b128 v[204:207], v185 offset:35840
	ds_read_b128 v[208:211], v185 offset:36864
	ds_read_b128 v[212:215], v185 offset:37888
	ds_read_b128 v[216:219], v185 offset:38912
	ds_read_b128 v[226:229], v185 offset:39936
	global_load_lds_dwordx4 v[236:237], off
	v_lshl_add_u64 v[236:237], s[72:73], 0, v[180:181]
	s_mov_b32 m0, s22
	s_nop 0
	global_load_lds_dwordx4 v[236:237], off
	s_waitcnt vmcnt(8)
	s_waitcnt lgkmcnt(0)
	s_barrier
	v_mfma_f32_16x16x32_bf16 v[2:5], v[132:135], v[164:167], v[2:5]
	v_mfma_f32_16x16x32_bf16 v[6:9], v[140:143], v[164:167], v[6:9]
	v_mfma_f32_16x16x32_bf16 v[10:13], v[132:135], v[196:199], v[10:13]
	v_mfma_f32_16x16x32_bf16 v[14:17], v[140:143], v[196:199], v[14:17]
	v_mfma_f32_16x16x32_bf16 v[18:21], v[132:135], v[208:211], v[18:21]
	v_mfma_f32_16x16x32_bf16 v[22:25], v[140:143], v[208:211], v[22:25]
	v_mfma_f32_16x16x32_bf16 v[28:31], v[132:135], v[216:219], v[28:31]
	v_mfma_f32_16x16x32_bf16 v[32:35], v[140:143], v[216:219], v[32:35]
	v_mfma_f32_16x16x32_bf16 v[2:5], v[136:139], v[192:195], v[2:5]
	v_mfma_f32_16x16x32_bf16 v[6:9], v[144:147], v[192:195], v[6:9]
	v_mfma_f32_16x16x32_bf16 v[10:13], v[136:139], v[204:207], v[10:13]
	v_mfma_f32_16x16x32_bf16 v[14:17], v[144:147], v[204:207], v[14:17]
	v_mfma_f32_16x16x32_bf16 v[18:21], v[136:139], v[212:215], v[18:21]
	v_mfma_f32_16x16x32_bf16 v[22:25], v[144:147], v[212:215], v[22:25]
	v_mfma_f32_16x16x32_bf16 v[28:31], v[136:139], v[226:229], v[28:31]
	v_mfma_f32_16x16x32_bf16 v[32:35], v[144:147], v[226:229], v[32:35]
	v_mfma_f32_16x16x32_bf16 v[36:39], v[148:151], v[164:167], v[36:39]
	v_mfma_f32_16x16x32_bf16 v[40:43], v[156:159], v[164:167], v[40:43]
	v_mfma_f32_16x16x32_bf16 v[44:47], v[148:151], v[196:199], v[44:47]
	v_mfma_f32_16x16x32_bf16 v[48:51], v[156:159], v[196:199], v[48:51]
	v_mfma_f32_16x16x32_bf16 v[52:55], v[148:151], v[208:211], v[52:55]
	v_mfma_f32_16x16x32_bf16 v[56:59], v[156:159], v[208:211], v[56:59]
	v_mfma_f32_16x16x32_bf16 v[60:63], v[148:151], v[216:219], v[60:63]
	v_mfma_f32_16x16x32_bf16 v[64:67], v[156:159], v[216:219], v[64:67]
	v_mfma_f32_16x16x32_bf16 v[36:39], v[152:155], v[192:195], v[36:39]
	v_mfma_f32_16x16x32_bf16 v[40:43], v[160:163], v[192:195], v[40:43]
	v_mfma_f32_16x16x32_bf16 v[44:47], v[152:155], v[204:207], v[44:47]
	v_mfma_f32_16x16x32_bf16 v[48:51], v[160:163], v[204:207], v[48:51]
	v_mfma_f32_16x16x32_bf16 v[52:55], v[152:155], v[212:215], v[52:55]
	v_mfma_f32_16x16x32_bf16 v[56:59], v[160:163], v[212:215], v[56:59]
	v_mfma_f32_16x16x32_bf16 v[60:63], v[152:155], v[226:229], v[60:63]
	v_mfma_f32_16x16x32_bf16 v[64:67], v[160:163], v[226:229], v[64:67]
	s_barrier
	s_add_i32 s12, s12, s8
	v_lshl_add_u64 v[220:221], v[220:221], 0, s[82:83]
	s_mov_b32 m0, s12
	ds_read_b128 v[164:167], v185 offset:49152
	ds_read_b128 v[192:195], v185 offset:50176
	ds_read_b128 v[196:199], v185 offset:51200
	ds_read_b128 v[204:207], v185 offset:52224
	ds_read_b128 v[208:211], v185 offset:53248
	ds_read_b128 v[212:215], v185 offset:54272
	ds_read_b128 v[216:219], v185 offset:55296
	ds_read_b128 v[226:229], v185 offset:56320
	global_load_lds_dwordx4 v[220:221], off
	s_add_i32 m0, s12, 0x2000
	s_add_u32 s72, s74, 0x40080
	v_lshl_add_u64 v[220:221], v[230:231], 0, s[82:83]
	s_addc_u32 s73, s75, 0
	s_add_i32 s12, s78, s8
	global_load_lds_dwordx4 v[220:221], off
	v_lshl_add_u64 v[220:221], s[72:73], 0, v[178:179]
	s_mov_b32 m0, s12
	s_nop 0
	global_load_lds_dwordx4 v[220:221], off
	v_lshl_add_u64 v[220:221], s[72:73], 0, v[182:183]
	s_add_i32 m0, s12, 0x2000
	s_nop 0
	global_load_lds_dwordx4 v[220:221], off
	v_lshl_add_u64 v[220:221], v[232:233], 0, s[82:83]
	s_mov_b32 m0, s46
	s_nop 0
	global_load_lds_dwordx4 v[220:221], off
	v_lshl_add_u64 v[220:221], v[234:235], 0, s[82:83]
	s_mov_b32 m0, s47
	s_nop 0
	global_load_lds_dwordx4 v[220:221], off
	s_waitcnt vmcnt(8)
	s_waitcnt lgkmcnt(0)
	s_barrier
	v_mfma_f32_16x16x32_bf16 v[68:71], v[132:135], v[164:167], v[68:71]
	v_mfma_f32_16x16x32_bf16 v[72:75], v[140:143], v[164:167], v[72:75]
	v_mfma_f32_16x16x32_bf16 v[76:79], v[132:135], v[196:199], v[76:79]
	v_mfma_f32_16x16x32_bf16 v[80:83], v[140:143], v[196:199], v[80:83]
	v_mfma_f32_16x16x32_bf16 v[84:87], v[132:135], v[208:211], v[84:87]
	v_mfma_f32_16x16x32_bf16 v[88:91], v[140:143], v[208:211], v[88:91]
	v_mfma_f32_16x16x32_bf16 v[92:95], v[132:135], v[216:219], v[92:95]
	v_mfma_f32_16x16x32_bf16 v[96:99], v[140:143], v[216:219], v[96:99]
	v_mfma_f32_16x16x32_bf16 v[68:71], v[136:139], v[192:195], v[68:71]
	v_mfma_f32_16x16x32_bf16 v[72:75], v[144:147], v[192:195], v[72:75]
	v_mfma_f32_16x16x32_bf16 v[76:79], v[136:139], v[204:207], v[76:79]
	v_mfma_f32_16x16x32_bf16 v[80:83], v[144:147], v[204:207], v[80:83]
	v_mfma_f32_16x16x32_bf16 v[84:87], v[136:139], v[212:215], v[84:87]
	v_mfma_f32_16x16x32_bf16 v[88:91], v[144:147], v[212:215], v[88:91]
	v_mfma_f32_16x16x32_bf16 v[92:95], v[136:139], v[226:229], v[92:95]
	v_mfma_f32_16x16x32_bf16 v[96:99], v[144:147], v[226:229], v[96:99]
	v_mfma_f32_16x16x32_bf16 v[100:103], v[148:151], v[164:167], v[100:103]
	v_mfma_f32_16x16x32_bf16 v[104:107], v[156:159], v[164:167], v[104:107]
	v_mfma_f32_16x16x32_bf16 v[108:111], v[148:151], v[196:199], v[108:111]
	v_mfma_f32_16x16x32_bf16 v[112:115], v[156:159], v[196:199], v[112:115]
	v_mfma_f32_16x16x32_bf16 v[116:119], v[148:151], v[208:211], v[116:119]
	v_mfma_f32_16x16x32_bf16 v[120:123], v[156:159], v[208:211], v[120:123]
	v_mfma_f32_16x16x32_bf16 v[124:127], v[148:151], v[216:219], v[124:127]
	v_mfma_f32_16x16x32_bf16 v[128:131], v[156:159], v[216:219], v[128:131]
	v_mfma_f32_16x16x32_bf16 v[100:103], v[152:155], v[192:195], v[100:103]
	v_mfma_f32_16x16x32_bf16 v[104:107], v[160:163], v[192:195], v[104:107]
	v_mfma_f32_16x16x32_bf16 v[108:111], v[152:155], v[204:207], v[108:111]
	v_mfma_f32_16x16x32_bf16 v[112:115], v[160:163], v[204:207], v[112:115]
	v_mfma_f32_16x16x32_bf16 v[116:119], v[152:155], v[212:215], v[116:119]
	v_mfma_f32_16x16x32_bf16 v[120:123], v[160:163], v[212:215], v[120:123]
	v_mfma_f32_16x16x32_bf16 v[124:127], v[152:155], v[226:229], v[124:127]
	v_mfma_f32_16x16x32_bf16 v[128:131], v[160:163], v[226:229], v[128:131]
	s_barrier
	s_add_i32 s61, s61, 2
	s_add_u32 s86, s86, 0x100
	s_addc_u32 s87, s87, 0
	s_add_u32 s35, s35, 0x100
	s_addc_u32 s59, s59, 0
	s_cmp_gt_u32 s61, 13
	s_cbranch_scc0 .LBB0_678
	s_and_b64 vcc, exec, s[26:27]
	s_cbranch_vccz .LBB0_681
	s_barrier

.LBB0_737:
	s_add_u32 s12, s60, 0xffea0080
	s_addc_u32 s58, s61, -1
	s_add_i32 s72, 0, 0x10000
	s_cmp_eq_u32 s55, 12
	s_cselect_b32 s77, s75, s58
	s_cselect_b32 s76, s74, s12
	v_add_u32_e32 v26, s72, v165
	s_cselect_b32 s59, s87, s53
	s_cselect_b32 s58, s86, s31
	s_add_i32 s12, 0, 0x14000
	s_waitcnt lgkmcnt(0)
	ds_read_b128 v[132:135], v26
	ds_read_b128 v[136:139], v26 offset:1024
	ds_read_b128 v[140:143], v26 offset:2048
	ds_read_b128 v[156:159], v26 offset:3072
	v_add_u32_e32 v26, s12, v165
	ds_read_b128 v[160:163], v26
	ds_read_b128 v[176:179], v26 offset:1024
	ds_read_b128 v[180:183], v26 offset:2048
	ds_read_b128 v[184:187], v26 offset:3072
	v_lshl_add_u64 v[220:221], s[60:61], 0, v[152:153]
	s_add_i32 m0, s11, 0xc000
	ds_read_b128 v[188:191], v167
	ds_read_b128 v[192:195], v167 offset:1024
	ds_read_b128 v[196:199], v167 offset:2048
	ds_read_b128 v[200:203], v167 offset:3072
	ds_read_b128 v[204:207], v167 offset:4096
	ds_read_b128 v[208:211], v167 offset:5120
	ds_read_b128 v[212:215], v167 offset:6144
	ds_read_b128 v[216:219], v167 offset:7168
	global_load_lds_dwordx4 v[220:221], off
	v_lshl_add_u64 v[220:221], s[60:61], 0, v[154:155]
	s_add_i32 m0, s11, 0xe000
	s_nop 0
	global_load_lds_dwordx4 v[220:221], off
	s_waitcnt vmcnt(8)
	s_waitcnt lgkmcnt(0)
	s_barrier
	v_mfma_f32_16x16x32_bf16 v[2:5], v[132:135], v[188:191], v[2:5]
	v_mfma_f32_16x16x32_bf16 v[6:9], v[140:143], v[188:191], v[6:9]
	v_mfma_f32_16x16x32_bf16 v[10:13], v[132:135], v[196:199], v[10:13]
	v_mfma_f32_16x16x32_bf16 v[14:17], v[140:143], v[196:199], v[14:17]
	v_mfma_f32_16x16x32_bf16 v[18:21], v[132:135], v[204:207], v[18:21]
	v_mfma_f32_16x16x32_bf16 v[22:25], v[140:143], v[204:207], v[22:25]
	v_mfma_f32_16x16x32_bf16 v[28:31], v[132:135], v[212:215], v[28:31]
	v_mfma_f32_16x16x32_bf16 v[32:35], v[140:143], v[212:215], v[32:35]
	v_mfma_f32_16x16x32_bf16 v[2:5], v[136:139], v[192:195], v[2:5]
	v_mfma_f32_16x16x32_bf16 v[6:9], v[156:159], v[192:195], v[6:9]
	v_mfma_f32_16x16x32_bf16 v[10:13], v[136:139], v[200:203], v[10:13]
	v_mfma_f32_16x16x32_bf16 v[14:17], v[156:159], v[200:203], v[14:17]
	v_mfma_f32_16x16x32_bf16 v[18:21], v[136:139], v[208:211], v[18:21]
	v_mfma_f32_16x16x32_bf16 v[22:25], v[156:159], v[208:211], v[22:25]
	v_mfma_f32_16x16x32_bf16 v[28:31], v[136:139], v[216:219], v[28:31]
	v_mfma_f32_16x16x32_bf16 v[32:35], v[156:159], v[216:219], v[32:35]
	v_mfma_f32_16x16x32_bf16 v[36:39], v[160:163], v[188:191], v[36:39]
	v_mfma_f32_16x16x32_bf16 v[40:43], v[180:183], v[188:191], v[40:43]
	v_mfma_f32_16x16x32_bf16 v[44:47], v[160:163], v[196:199], v[44:47]
	v_mfma_f32_16x16x32_bf16 v[48:51], v[180:183], v[196:199], v[48:51]
	v_mfma_f32_16x16x32_bf16 v[52:55], v[160:163], v[204:207], v[52:55]
	v_mfma_f32_16x16x32_bf16 v[56:59], v[180:183], v[204:207], v[56:59]
	v_mfma_f32_16x16x32_bf16 v[60:63], v[160:163], v[212:215], v[60:63]
	v_mfma_f32_16x16x32_bf16 v[64:67], v[180:183], v[212:215], v[64:67]
	v_mfma_f32_16x16x32_bf16 v[36:39], v[176:179], v[192:195], v[36:39]
	v_mfma_f32_16x16x32_bf16 v[40:43], v[184:187], v[192:195], v[40:43]
	v_mfma_f32_16x16x32_bf16 v[44:47], v[176:179], v[200:203], v[44:47]
	v_mfma_f32_16x16x32_bf16 v[48:51], v[184:187], v[200:203], v[48:51]
	v_mfma_f32_16x16x32_bf16 v[52:55], v[176:179], v[208:211], v[52:55]
	v_mfma_f32_16x16x32_bf16 v[56:59], v[184:187], v[208:211], v[56:59]
	v_mfma_f32_16x16x32_bf16 v[60:63], v[176:179], v[216:219], v[60:63]
	v_mfma_f32_16x16x32_bf16 v[64:67], v[184:187], v[216:219], v[64:67]
	s_barrier
	s_add_i32 s72, s72, s8
	v_lshl_add_u64 v[220:221], s[58:59], 0, v[146:147]
	s_mov_b32 m0, s72
	ds_read_b128 v[188:191], v167 offset:16384
	ds_read_b128 v[192:195], v167 offset:17408
	ds_read_b128 v[196:199], v167 offset:18432
	ds_read_b128 v[200:203], v167 offset:19456
	ds_read_b128 v[204:207], v167 offset:20480
	ds_read_b128 v[208:211], v167 offset:21504
	ds_read_b128 v[212:215], v167 offset:22528
	ds_read_b128 v[216:219], v167 offset:23552
	global_load_lds_dwordx4 v[220:221], off
	s_add_i32 m0, s72, 0x2000
	s_add_u32 s72, s58, 0x40000
	v_lshl_add_u64 v[226:227], s[58:59], 0, v[150:151]
	s_addc_u32 s73, s59, 0
	s_add_i32 s12, s12, s8
	global_load_lds_dwordx4 v[226:227], off
	v_lshl_add_u64 v[228:229], s[72:73], 0, v[146:147]
	s_mov_b32 m0, s12
	v_lshl_add_u64 v[230:231], s[76:77], 0, v[148:149]
	global_load_lds_dwordx4 v[228:229], off
	v_lshl_add_u64 v[228:229], s[72:73], 0, v[150:151]
	s_add_i32 m0, s12, 0x2000
	s_nop 0
	global_load_lds_dwordx4 v[228:229], off
	v_lshl_add_u64 v[228:229], s[76:77], 0, v[144:145]
	s_mov_b32 m0, s11
	s_nop 0
	global_load_lds_dwordx4 v[228:229], off
	s_mov_b32 m0, s16
	s_nop 0
	global_load_lds_dwordx4 v[230:231], off
	s_waitcnt vmcnt(8)
	s_waitcnt lgkmcnt(0)
	s_barrier
	v_mfma_f32_16x16x32_bf16 v[68:71], v[132:135], v[188:191], v[68:71]
	v_mfma_f32_16x16x32_bf16 v[72:75], v[140:143], v[188:191], v[72:75]
	v_mfma_f32_16x16x32_bf16 v[76:79], v[132:135], v[196:199], v[76:79]
	v_mfma_f32_16x16x32_bf16 v[80:83], v[140:143], v[196:199], v[80:83]
	v_mfma_f32_16x16x32_bf16 v[84:87], v[132:135], v[204:207], v[84:87]
	v_mfma_f32_16x16x32_bf16 v[88:91], v[140:143], v[204:207], v[88:91]
	v_mfma_f32_16x16x32_bf16 v[92:95], v[132:135], v[212:215], v[92:95]
	v_mfma_f32_16x16x32_bf16 v[96:99], v[140:143], v[212:215], v[96:99]
	v_mfma_f32_16x16x32_bf16 v[68:71], v[136:139], v[192:195], v[68:71]
	v_mfma_f32_16x16x32_bf16 v[72:75], v[156:159], v[192:195], v[72:75]
	v_mfma_f32_16x16x32_bf16 v[76:79], v[136:139], v[200:203], v[76:79]
	v_mfma_f32_16x16x32_bf16 v[80:83], v[156:159], v[200:203], v[80:83]
	v_mfma_f32_16x16x32_bf16 v[84:87], v[136:139], v[208:211], v[84:87]
	v_mfma_f32_16x16x32_bf16 v[88:91], v[156:159], v[208:211], v[88:91]
	v_mfma_f32_16x16x32_bf16 v[92:95], v[136:139], v[216:219], v[92:95]
	v_mfma_f32_16x16x32_bf16 v[96:99], v[156:159], v[216:219], v[96:99]
	v_mfma_f32_16x16x32_bf16 v[100:103], v[160:163], v[188:191], v[100:103]
	v_mfma_f32_16x16x32_bf16 v[104:107], v[180:183], v[188:191], v[104:107]
	v_mfma_f32_16x16x32_bf16 v[108:111], v[160:163], v[196:199], v[108:111]
	v_mfma_f32_16x16x32_bf16 v[112:115], v[180:183], v[196:199], v[112:115]
	v_mfma_f32_16x16x32_bf16 v[116:119], v[160:163], v[204:207], v[116:119]
	v_mfma_f32_16x16x32_bf16 v[120:123], v[180:183], v[204:207], v[120:123]
	v_mfma_f32_16x16x32_bf16 v[124:127], v[160:163], v[212:215], v[124:127]
	v_mfma_f32_16x16x32_bf16 v[128:131], v[180:183], v[212:215], v[128:131]
	v_mfma_f32_16x16x32_bf16 v[100:103], v[176:179], v[192:195], v[100:103]
	v_mfma_f32_16x16x32_bf16 v[104:107], v[184:187], v[192:195], v[104:107]
	v_mfma_f32_16x16x32_bf16 v[108:111], v[176:179], v[200:203], v[108:111]
	v_mfma_f32_16x16x32_bf16 v[112:115], v[184:187], v[200:203], v[112:115]
	v_mfma_f32_16x16x32_bf16 v[116:119], v[176:179], v[208:211], v[116:119]
	v_mfma_f32_16x16x32_bf16 v[120:123], v[184:187], v[208:211], v[120:123]
	v_mfma_f32_16x16x32_bf16 v[124:127], v[176:179], v[216:219], v[124:127]
	v_mfma_f32_16x16x32_bf16 v[128:131], v[184:187], v[216:219], v[128:131]
	s_barrier
	s_add_i32 s12, 0, 0x18000
	v_add_u32_e32 v26, s12, v165
	s_add_i32 s79, 0, 0x1c000
	ds_read_b128 v[132:135], v26
	ds_read_b128 v[136:139], v26 offset:1024
	ds_read_b128 v[140:143], v26 offset:2048
	ds_read_b128 v[156:159], v26 offset:3072
	v_add_u32_e32 v26, s79, v165
	ds_read_b128 v[160:163], v26
	ds_read_b128 v[176:179], v26 offset:1024
	ds_read_b128 v[180:183], v26 offset:2048
	ds_read_b128 v[184:187], v26 offset:3072
	s_add_u32 s72, s76, 0x160000
	s_addc_u32 s73, s77, 0
	s_mov_b32 m0, s17
	v_lshl_add_u64 v[232:233], s[72:73], 0, v[144:145]
	ds_read_b128 v[188:191], v167 offset:32768
	ds_read_b128 v[192:195], v167 offset:33792
	ds_read_b128 v[196:199], v167 offset:34816
	ds_read_b128 v[200:203], v167 offset:35840
	ds_read_b128 v[204:207], v167 offset:36864
	ds_read_b128 v[208:211], v167 offset:37888
	ds_read_b128 v[212:215], v167 offset:38912
	ds_read_b128 v[216:219], v167 offset:39936
	global_load_lds_dwordx4 v[232:233], off
	v_lshl_add_u64 v[232:233], s[72:73], 0, v[148:149]
	s_mov_b32 m0, s22
	s_nop 0
	global_load_lds_dwordx4 v[232:233], off
	s_waitcnt vmcnt(8)
	s_waitcnt lgkmcnt(0)
	s_barrier
	v_mfma_f32_16x16x32_bf16 v[2:5], v[132:135], v[188:191], v[2:5]
	v_mfma_f32_16x16x32_bf16 v[6:9], v[140:143], v[188:191], v[6:9]
	v_mfma_f32_16x16x32_bf16 v[10:13], v[132:135], v[196:199], v[10:13]
	v_mfma_f32_16x16x32_bf16 v[14:17], v[140:143], v[196:199], v[14:17]
	v_mfma_f32_16x16x32_bf16 v[18:21], v[132:135], v[204:207], v[18:21]
	v_mfma_f32_16x16x32_bf16 v[22:25], v[140:143], v[204:207], v[22:25]
	v_mfma_f32_16x16x32_bf16 v[28:31], v[132:135], v[212:215], v[28:31]
	v_mfma_f32_16x16x32_bf16 v[32:35], v[140:143], v[212:215], v[32:35]
	v_mfma_f32_16x16x32_bf16 v[2:5], v[136:139], v[192:195], v[2:5]
	v_mfma_f32_16x16x32_bf16 v[6:9], v[156:159], v[192:195], v[6:9]
	v_mfma_f32_16x16x32_bf16 v[10:13], v[136:139], v[200:203], v[10:13]
	v_mfma_f32_16x16x32_bf16 v[14:17], v[156:159], v[200:203], v[14:17]
	v_mfma_f32_16x16x32_bf16 v[18:21], v[136:139], v[208:211], v[18:21]
	v_mfma_f32_16x16x32_bf16 v[22:25], v[156:159], v[208:211], v[22:25]
	v_mfma_f32_16x16x32_bf16 v[28:31], v[136:139], v[216:219], v[28:31]
	v_mfma_f32_16x16x32_bf16 v[32:35], v[156:159], v[216:219], v[32:35]
	v_mfma_f32_16x16x32_bf16 v[36:39], v[160:163], v[188:191], v[36:39]
	v_mfma_f32_16x16x32_bf16 v[40:43], v[180:183], v[188:191], v[40:43]
	v_mfma_f32_16x16x32_bf16 v[44:47], v[160:163], v[196:199], v[44:47]
	v_mfma_f32_16x16x32_bf16 v[48:51], v[180:183], v[196:199], v[48:51]
	v_mfma_f32_16x16x32_bf16 v[52:55], v[160:163], v[204:207], v[52:55]
	v_mfma_f32_16x16x32_bf16 v[56:59], v[180:183], v[204:207], v[56:59]
	v_mfma_f32_16x16x32_bf16 v[60:63], v[160:163], v[212:215], v[60:63]
	v_mfma_f32_16x16x32_bf16 v[64:67], v[180:183], v[212:215], v[64:67]
	v_mfma_f32_16x16x32_bf16 v[36:39], v[176:179], v[192:195], v[36:39]
	v_mfma_f32_16x16x32_bf16 v[40:43], v[184:187], v[192:195], v[40:43]
	v_mfma_f32_16x16x32_bf16 v[44:47], v[176:179], v[200:203], v[44:47]
	v_mfma_f32_16x16x32_bf16 v[48:51], v[184:187], v[200:203], v[48:51]
	v_mfma_f32_16x16x32_bf16 v[52:55], v[176:179], v[208:211], v[52:55]
	v_mfma_f32_16x16x32_bf16 v[56:59], v[184:187], v[208:211], v[56:59]
	v_mfma_f32_16x16x32_bf16 v[60:63], v[176:179], v[216:219], v[60:63]
	v_mfma_f32_16x16x32_bf16 v[64:67], v[184:187], v[216:219], v[64:67]
	s_barrier
	s_add_i32 s12, s12, s8
	v_lshl_add_u64 v[220:221], v[220:221], 0, s[82:83]
	s_mov_b32 m0, s12
	ds_read_b128 v[188:191], v167 offset:49152
	ds_read_b128 v[192:195], v167 offset:50176
	ds_read_b128 v[196:199], v167 offset:51200
	ds_read_b128 v[200:203], v167 offset:52224
	ds_read_b128 v[204:207], v167 offset:53248
	ds_read_b128 v[208:211], v167 offset:54272
	ds_read_b128 v[212:215], v167 offset:55296
	ds_read_b128 v[216:219], v167 offset:56320
	global_load_lds_dwordx4 v[220:221], off
	s_add_i32 m0, s12, 0x2000
	s_add_u32 s58, s58, 0x40080
	v_lshl_add_u64 v[220:221], v[226:227], 0, s[82:83]
	s_addc_u32 s59, s59, 0
	s_add_i32 s12, s79, s8
	global_load_lds_dwordx4 v[220:221], off
	v_lshl_add_u64 v[220:221], s[58:59], 0, v[146:147]
	s_mov_b32 m0, s12
	s_nop 0
	global_load_lds_dwordx4 v[220:221], off
	v_lshl_add_u64 v[220:221], s[58:59], 0, v[150:151]
	s_add_i32 m0, s12, 0x2000
	s_nop 0
	global_load_lds_dwordx4 v[220:221], off
	v_lshl_add_u64 v[220:221], v[228:229], 0, s[82:83]
	s_mov_b32 m0, s46
	s_nop 0
	global_load_lds_dwordx4 v[220:221], off
	v_lshl_add_u64 v[220:221], v[230:231], 0, s[82:83]
	s_mov_b32 m0, s47
	s_nop 0
	global_load_lds_dwordx4 v[220:221], off
	s_waitcnt vmcnt(8)
	s_waitcnt lgkmcnt(0)
	s_barrier
	v_mfma_f32_16x16x32_bf16 v[68:71], v[132:135], v[188:191], v[68:71]
	v_mfma_f32_16x16x32_bf16 v[72:75], v[140:143], v[188:191], v[72:75]
	v_mfma_f32_16x16x32_bf16 v[76:79], v[132:135], v[196:199], v[76:79]
	v_mfma_f32_16x16x32_bf16 v[80:83], v[140:143], v[196:199], v[80:83]
	v_mfma_f32_16x16x32_bf16 v[84:87], v[132:135], v[204:207], v[84:87]
	v_mfma_f32_16x16x32_bf16 v[88:91], v[140:143], v[204:207], v[88:91]
	v_mfma_f32_16x16x32_bf16 v[92:95], v[132:135], v[212:215], v[92:95]
	v_mfma_f32_16x16x32_bf16 v[96:99], v[140:143], v[212:215], v[96:99]
	v_mfma_f32_16x16x32_bf16 v[68:71], v[136:139], v[192:195], v[68:71]
	v_mfma_f32_16x16x32_bf16 v[72:75], v[156:159], v[192:195], v[72:75]
	v_mfma_f32_16x16x32_bf16 v[76:79], v[136:139], v[200:203], v[76:79]
	v_mfma_f32_16x16x32_bf16 v[80:83], v[156:159], v[200:203], v[80:83]
	v_mfma_f32_16x16x32_bf16 v[84:87], v[136:139], v[208:211], v[84:87]
	v_mfma_f32_16x16x32_bf16 v[88:91], v[156:159], v[208:211], v[88:91]
	v_mfma_f32_16x16x32_bf16 v[92:95], v[136:139], v[216:219], v[92:95]
	v_mfma_f32_16x16x32_bf16 v[96:99], v[156:159], v[216:219], v[96:99]
	v_mfma_f32_16x16x32_bf16 v[100:103], v[160:163], v[188:191], v[100:103]
	v_mfma_f32_16x16x32_bf16 v[104:107], v[180:183], v[188:191], v[104:107]
	v_mfma_f32_16x16x32_bf16 v[108:111], v[160:163], v[196:199], v[108:111]
	v_mfma_f32_16x16x32_bf16 v[112:115], v[180:183], v[196:199], v[112:115]
	v_mfma_f32_16x16x32_bf16 v[116:119], v[160:163], v[204:207], v[116:119]
	v_mfma_f32_16x16x32_bf16 v[120:123], v[180:183], v[204:207], v[120:123]
	v_mfma_f32_16x16x32_bf16 v[124:127], v[160:163], v[212:215], v[124:127]
	v_mfma_f32_16x16x32_bf16 v[128:131], v[180:183], v[212:215], v[128:131]
	v_mfma_f32_16x16x32_bf16 v[100:103], v[176:179], v[192:195], v[100:103]
	v_mfma_f32_16x16x32_bf16 v[104:107], v[184:187], v[192:195], v[104:107]
	v_mfma_f32_16x16x32_bf16 v[108:111], v[176:179], v[200:203], v[108:111]
	v_mfma_f32_16x16x32_bf16 v[112:115], v[184:187], v[200:203], v[112:115]
	v_mfma_f32_16x16x32_bf16 v[116:119], v[176:179], v[208:211], v[116:119]
	v_mfma_f32_16x16x32_bf16 v[120:123], v[184:187], v[208:211], v[120:123]
	v_mfma_f32_16x16x32_bf16 v[124:127], v[176:179], v[216:219], v[124:127]
	v_mfma_f32_16x16x32_bf16 v[128:131], v[184:187], v[216:219], v[128:131]
	s_barrier
	s_add_i32 s55, s55, 2
	s_add_u32 s60, s60, 0x100
	s_addc_u32 s61, s61, 0
	s_add_u32 s31, s31, 0x100
	s_addc_u32 s53, s53, 0
	s_cmp_gt_u32 s55, 13
	s_cbranch_scc0 .LBB0_737
	s_and_b64 vcc, exec, s[26:27]
	s_cbranch_vccz .LBB0_740
	s_barrier
